# MLA-Q epilogue stat/rope loads batched and counted waits; GEMM first K-iteration peeled with SrcC=0 (no zeroing movs); P0 c1 dot loop batched
# speedup vs baseline: 1.0009x; 1.0009x over previous
; DI void p0_prologue(int wv, const Params& P, LAS unsigned char* lds) {
;     ...
;     {
;         float* c1 = (float*)(P.ws + WS_C1);
;         for (int o = gw; o < 512; o += NGW) {
;             const int j = o >> 8, kv = (o >> 7) & 1, col = o & 127;
;             const float* pos = P.in[kv ? 22 : 19] + (size_t)j * 2048; const float* w1 = P.in[kv ? 23 : 20] + (size_t)j * 2048 * 128;
;             float s = 0.f;
;             for (int i = lane; i < 2048; i += 64) s += pos[i] * w1[(size_t)i * 128 + col];
;             s = wave_sum(s);
;             if (lane == 0) c1[o] = s;
;         }
.LBB0_1728:
	global_load_dword v21, v[6:7], off
	global_load_dword v37, v[8:9], off
	v_lshl_add_u64 v[6:7], v[6:7], 0, s[2:3]
	v_lshl_add_u64 v[8:9], v[8:9], 0, s[4:5]
	global_load_dword v22, v[6:7], off
	global_load_dword v38, v[8:9], off
	v_lshl_add_u64 v[6:7], v[6:7], 0, s[2:3]
	v_lshl_add_u64 v[8:9], v[8:9], 0, s[4:5]
	global_load_dword v23, v[6:7], off
	global_load_dword v39, v[8:9], off
	v_lshl_add_u64 v[6:7], v[6:7], 0, s[2:3]
	v_lshl_add_u64 v[8:9], v[8:9], 0, s[4:5]
	global_load_dword v24, v[6:7], off
	global_load_dword v40, v[8:9], off
	v_lshl_add_u64 v[6:7], v[6:7], 0, s[2:3]
	v_lshl_add_u64 v[8:9], v[8:9], 0, s[4:5]
	global_load_dword v25, v[6:7], off
	global_load_dword v41, v[8:9], off
	v_lshl_add_u64 v[6:7], v[6:7], 0, s[2:3]
	v_lshl_add_u64 v[8:9], v[8:9], 0, s[4:5]
	global_load_dword v26, v[6:7], off
	global_load_dword v42, v[8:9], off
	v_lshl_add_u64 v[6:7], v[6:7], 0, s[2:3]
	v_lshl_add_u64 v[8:9], v[8:9], 0, s[4:5]
	global_load_dword v27, v[6:7], off
	global_load_dword v43, v[8:9], off
	v_lshl_add_u64 v[6:7], v[6:7], 0, s[2:3]
	v_lshl_add_u64 v[8:9], v[8:9], 0, s[4:5]
	global_load_dword v28, v[6:7], off
	global_load_dword v44, v[8:9], off
	v_lshl_add_u64 v[6:7], v[6:7], 0, s[2:3]
	v_lshl_add_u64 v[8:9], v[8:9], 0, s[4:5]
	global_load_dword v29, v[6:7], off
	global_load_dword v45, v[8:9], off
	v_lshl_add_u64 v[6:7], v[6:7], 0, s[2:3]
	v_lshl_add_u64 v[8:9], v[8:9], 0, s[4:5]
	global_load_dword v30, v[6:7], off
	global_load_dword v46, v[8:9], off
	v_lshl_add_u64 v[6:7], v[6:7], 0, s[2:3]
	v_lshl_add_u64 v[8:9], v[8:9], 0, s[4:5]
	global_load_dword v31, v[6:7], off
	global_load_dword v47, v[8:9], off
	v_lshl_add_u64 v[6:7], v[6:7], 0, s[2:3]
	v_lshl_add_u64 v[8:9], v[8:9], 0, s[4:5]
	global_load_dword v32, v[6:7], off
	global_load_dword v48, v[8:9], off
	v_lshl_add_u64 v[6:7], v[6:7], 0, s[2:3]
	v_lshl_add_u64 v[8:9], v[8:9], 0, s[4:5]
	global_load_dword v33, v[6:7], off
	global_load_dword v49, v[8:9], off
	v_lshl_add_u64 v[6:7], v[6:7], 0, s[2:3]
	v_lshl_add_u64 v[8:9], v[8:9], 0, s[4:5]
	global_load_dword v34, v[6:7], off
	global_load_dword v50, v[8:9], off
	v_lshl_add_u64 v[6:7], v[6:7], 0, s[2:3]
	v_lshl_add_u64 v[8:9], v[8:9], 0, s[4:5]
	global_load_dword v35, v[6:7], off
	global_load_dword v51, v[8:9], off
	v_lshl_add_u64 v[6:7], v[6:7], 0, s[2:3]
	v_lshl_add_u64 v[8:9], v[8:9], 0, s[4:5]
	global_load_dword v36, v[6:7], off
	global_load_dword v52, v[8:9], off
	v_lshl_add_u64 v[6:7], v[6:7], 0, s[2:3]
	v_lshl_add_u64 v[8:9], v[8:9], 0, s[4:5]
	s_waitcnt vmcnt(30)
	v_fmac_f32_e32 v17, v21, v37
	s_waitcnt vmcnt(28)
	v_fmac_f32_e32 v17, v22, v38
	s_waitcnt vmcnt(26)
	v_fmac_f32_e32 v17, v23, v39
	s_waitcnt vmcnt(24)
	v_fmac_f32_e32 v17, v24, v40
	s_waitcnt vmcnt(22)
	v_fmac_f32_e32 v17, v25, v41
	s_waitcnt vmcnt(20)
	v_fmac_f32_e32 v17, v26, v42
	s_waitcnt vmcnt(18)
	v_fmac_f32_e32 v17, v27, v43
	s_waitcnt vmcnt(16)
	v_fmac_f32_e32 v17, v28, v44
	s_waitcnt vmcnt(14)
	v_fmac_f32_e32 v17, v29, v45
	s_waitcnt vmcnt(12)
	v_fmac_f32_e32 v17, v30, v46
	s_waitcnt vmcnt(10)
	v_fmac_f32_e32 v17, v31, v47
	s_waitcnt vmcnt(8)
	v_fmac_f32_e32 v17, v32, v48
	s_waitcnt vmcnt(6)
	v_fmac_f32_e32 v17, v33, v49
	s_waitcnt vmcnt(4)
	v_fmac_f32_e32 v17, v34, v50
	s_waitcnt vmcnt(2)
	v_fmac_f32_e32 v17, v35, v51
	s_waitcnt vmcnt(0)
; DI void p0_prologue(int wv, const Params& P, LAS unsigned char* lds) {
;     ...
;     {
;         float* c1 = (float*)(P.ws + WS_C1);
;         for (int o = gw; o < 512; o += NGW) {
;             const int j = o >> 8, kv = (o >> 7) & 1, col = o & 127;
;             const float* pos = P.in[kv ? 22 : 19] + (size_t)j * 2048; const float* w1 = P.in[kv ? 23 : 20] + (size_t)j * 2048 * 128;
;             float s = 0.f;
;             for (int i = lane; i < 2048; i += 64) s += pos[i] * w1[(size_t)i * 128 + col];
;             s = wave_sum(s);
;             if (lane == 0) c1[o] = s;
;         }
	v_fmac_f32_e32 v17, v36, v52
	global_load_dword v21, v[6:7], off
	global_load_dword v37, v[8:9], off
	v_lshl_add_u64 v[6:7], v[6:7], 0, s[2:3]
	v_lshl_add_u64 v[8:9], v[8:9], 0, s[4:5]
	global_load_dword v22, v[6:7], off
	global_load_dword v38, v[8:9], off
	v_lshl_add_u64 v[6:7], v[6:7], 0, s[2:3]
	v_lshl_add_u64 v[8:9], v[8:9], 0, s[4:5]
	global_load_dword v23, v[6:7], off
	global_load_dword v39, v[8:9], off
	v_lshl_add_u64 v[6:7], v[6:7], 0, s[2:3]
	v_lshl_add_u64 v[8:9], v[8:9], 0, s[4:5]
	global_load_dword v24, v[6:7], off
	global_load_dword v40, v[8:9], off
	v_lshl_add_u64 v[6:7], v[6:7], 0, s[2:3]
	v_lshl_add_u64 v[8:9], v[8:9], 0, s[4:5]
	global_load_dword v25, v[6:7], off
	global_load_dword v41, v[8:9], off
	v_lshl_add_u64 v[6:7], v[6:7], 0, s[2:3]
	v_lshl_add_u64 v[8:9], v[8:9], 0, s[4:5]
	global_load_dword v26, v[6:7], off
	global_load_dword v42, v[8:9], off
	v_lshl_add_u64 v[6:7], v[6:7], 0, s[2:3]
	v_lshl_add_u64 v[8:9], v[8:9], 0, s[4:5]
	global_load_dword v27, v[6:7], off
	global_load_dword v43, v[8:9], off
	v_lshl_add_u64 v[6:7], v[6:7], 0, s[2:3]
	v_lshl_add_u64 v[8:9], v[8:9], 0, s[4:5]
	global_load_dword v28, v[6:7], off
	global_load_dword v44, v[8:9], off
	v_lshl_add_u64 v[6:7], v[6:7], 0, s[2:3]
	v_lshl_add_u64 v[8:9], v[8:9], 0, s[4:5]
	global_load_dword v29, v[6:7], off
	global_load_dword v45, v[8:9], off
	v_lshl_add_u64 v[6:7], v[6:7], 0, s[2:3]
	v_lshl_add_u64 v[8:9], v[8:9], 0, s[4:5]
	global_load_dword v30, v[6:7], off
	global_load_dword v46, v[8:9], off
	v_lshl_add_u64 v[6:7], v[6:7], 0, s[2:3]
	v_lshl_add_u64 v[8:9], v[8:9], 0, s[4:5]
	global_load_dword v31, v[6:7], off
	global_load_dword v47, v[8:9], off
	v_lshl_add_u64 v[6:7], v[6:7], 0, s[2:3]
	v_lshl_add_u64 v[8:9], v[8:9], 0, s[4:5]
	global_load_dword v32, v[6:7], off
	global_load_dword v48, v[8:9], off
	v_lshl_add_u64 v[6:7], v[6:7], 0, s[2:3]
	v_lshl_add_u64 v[8:9], v[8:9], 0, s[4:5]
	global_load_dword v33, v[6:7], off
	global_load_dword v49, v[8:9], off
	v_lshl_add_u64 v[6:7], v[6:7], 0, s[2:3]
	v_lshl_add_u64 v[8:9], v[8:9], 0, s[4:5]
	global_load_dword v34, v[6:7], off
	global_load_dword v50, v[8:9], off
	v_lshl_add_u64 v[6:7], v[6:7], 0, s[2:3]
	v_lshl_add_u64 v[8:9], v[8:9], 0, s[4:5]
	global_load_dword v35, v[6:7], off
	global_load_dword v51, v[8:9], off
	v_lshl_add_u64 v[6:7], v[6:7], 0, s[2:3]
	v_lshl_add_u64 v[8:9], v[8:9], 0, s[4:5]
	global_load_dword v36, v[6:7], off
	global_load_dword v52, v[8:9], off
	v_lshl_add_u64 v[6:7], v[6:7], 0, s[2:3]
	v_lshl_add_u64 v[8:9], v[8:9], 0, s[4:5]
	s_waitcnt vmcnt(30)
	v_fmac_f32_e32 v17, v21, v37
	s_waitcnt vmcnt(28)
	v_fmac_f32_e32 v17, v22, v38
	s_waitcnt vmcnt(26)
	v_fmac_f32_e32 v17, v23, v39
	s_waitcnt vmcnt(24)
	v_fmac_f32_e32 v17, v24, v40
	s_waitcnt vmcnt(22)
	v_fmac_f32_e32 v17, v25, v41
	s_waitcnt vmcnt(20)
	v_fmac_f32_e32 v17, v26, v42
	s_waitcnt vmcnt(18)
	v_fmac_f32_e32 v17, v27, v43
	s_waitcnt vmcnt(16)
	v_fmac_f32_e32 v17, v28, v44
	s_waitcnt vmcnt(14)
	v_fmac_f32_e32 v17, v29, v45
	s_waitcnt vmcnt(12)
	v_fmac_f32_e32 v17, v30, v46
	s_waitcnt vmcnt(10)
	v_fmac_f32_e32 v17, v31, v47
	s_waitcnt vmcnt(8)
	v_fmac_f32_e32 v17, v32, v48
	s_waitcnt vmcnt(6)
	v_fmac_f32_e32 v17, v33, v49
	s_waitcnt vmcnt(4)
	v_fmac_f32_e32 v17, v34, v50
	s_waitcnt vmcnt(2)
	v_fmac_f32_e32 v17, v35, v51
	s_waitcnt vmcnt(0)
	v_fmac_f32_e32 v17, v36, v52
	s_or_b64 exec, exec, s[14:15]
	ds_bpermute_b32 v6, v10, v17
	s_waitcnt lgkmcnt(0)
	v_add_f32_e32 v6, v17, v6
	ds_bpermute_b32 v7, v11, v6
	s_waitcnt lgkmcnt(0)
	v_add_f32_e32 v6, v6, v7
	ds_bpermute_b32 v7, v12, v6
	s_waitcnt lgkmcnt(0)
	v_add_f32_e32 v6, v6, v7
	ds_bpermute_b32 v7, v13, v6
	s_waitcnt lgkmcnt(0)
	v_add_f32_e32 v6, v6, v7
	ds_bpermute_b32 v7, v14, v6
	s_waitcnt lgkmcnt(0)
	v_add_f32_e32 v6, v6, v7
	ds_bpermute_b32 v7, v15, v6
	s_and_saveexec_b64 s[0:1], vcc
	s_cbranch_execz .LBB0_1726
	s_ashr_i32 s7, s6, 31
	s_lshl_b64 s[14:15], s[6:7], 2
	s_add_u32 s14, s16, s14
	s_waitcnt lgkmcnt(0)
	v_add_f32_e32 v6, v6, v7
	s_addc_u32 s15, s17, s15
	global_store_dword v3, v6, s[14:15]
	s_branch .LBB0_1726

; #define PG8_STAGE(bufoff, gbase, voff) do { const char* _gb = (const char*)(gbase); asm volatile("" : "+s"(_gb)); _Pragma("unroll") for (int _i = 0; _i < 2; ++_i) { \
;         unsigned _vo = (voff)[_i]; asm volatile("" : "+v"(_vo));     \
;         __builtin_amdgcn_global_load_lds((const unsigned*)(_gb + _vo), (LAS unsigned*)(lds + (bufoff) + ldsw + _i * 8192), 16, 0, 0); } } while (0)
; #define PG8_LDA(dst, b, h) do { _Pragma("unroll") for (int m = 0; m < 4; ++m) _Pragma("unroll") for (int k = 0; k < 2; ++k) dst[m][k] = *(const LAS bf16x8*)(lds + PG8_SA(b, h) + aoff + m * 2048 + k * 1024); } while (0)
; template <class Epi, class Sched>
; DI void gemm_phase(int wv, LAS unsigned char* lds, const Gemm g, const Sched& S, const Epi& E) {
;     ...
;     const char* cA = (const char*)g.A + (size_t)cur.pm * tstepA; const char* cB = (const char*)g.Bt + (size_t)cur.pn * tstepB;
;     float rsn[2][4];
;     if constexpr (epi_prefetch<Epi>::value) E.pre(cur, wr, wc, fr, fq, rsn);
;     PG8_STAGE(PG8_SB(0, 0), cB, voffB); PG8_STAGE(PG8_SB(0, 1), cB + hstepB, voffB); PG8_STAGE(PG8_SA(0, 0), cA, voffA); PG8_STAGE(PG8_SA(0, 1), cA + hstepA, voffA);
;     if (wr == 1) PG8_BAR;
;     PG8_WAIT_V(2); PG8_BAR;
;     PG8_STAGE(PG8_SB(1, 0), cB + kstep, voffB); PG8_STAGE(PG8_SA(1, 0), cA + kstep, voffA); PG8_STAGE(PG8_SB(1, 1), cB + hstepB + kstep, voffB);
;     PG8_WAIT_V(6); PG8_BAR;
;     for (;;) {
;         const bool has_next = S.next(ui + 1, nxt);
;         const char* nA = has_next ? (const char*)g.A + (size_t)nxt.pm * tstepA : cA; const char* nB = has_next ? (const char*)g.Bt + (size_t)nxt.pn * tstepB : cB;
; #pragma nounroll
;         for (int t = 0; t < nt; t += 2) {
;             const bool last = (t == nt - 2);
;             const char* a1 = cA + (size_t)(t + 1) * kstep;
;             const char* a2 = last ? nA : cA + (size_t)(t + 2) * kstep; const char* b2 = last ? nB : cB + (size_t)(t + 2) * kstep;
;             const char* a3 = a2 + kstep; const char* b3 = b2 + kstep;
;             PG8_LDB(B0, 0, 0); PG8_LDB(B1, 0, 1); PG8_SCHED; PG8_LDA(At, 0, 0); PG8_STAGE(PG8_SA(1, 1), a1 + hstepA, voffA);
;             PG8_WAIT_V(8); PG8_WAIT_L(0); PG8_BAR; PG8_MMA(0, 0, At, B0); PG8_MMA(0, 1, At, B1); PG8_BAR; PG8_SCHED;
;             PG8_LDA(At, 0, 1); PG8_STAGE(PG8_SB(0, 0), b2, voffB); PG8_STAGE(PG8_SB(0, 1), b2 + hstepB, voffB); PG8_STAGE(PG8_SA(0, 0), a2, voffA);
.LBB0_1816:
	s_ashr_i32 s15, s14, 31
	s_lshl_b64 s[18:19], s[14:15], 19
	s_add_u32 s18, s34, s18
	s_addc_u32 s19, s35, s19
	s_and_b64 s[20:21], s[24:25], exec
	s_cselect_b32 s1, s19, s3
	s_cselect_b32 s23, s18, s2
	s_ashr_i32 s17, s16, 31
	s_lshl_b64 s[20:21], s[16:17], 19
	s_add_u32 s20, s36, s20
	s_addc_u32 s21, s37, s21
	s_and_b64 s[28:29], s[24:25], exec
	s_cselect_b32 s17, s21, s27
	s_cselect_b32 s55, s20, s26
	s_add_u32 s56, s26, 0x100
	s_addc_u32 s57, s27, 0
	s_add_u32 s2, s2, 0x40080
	s_addc_u32 s3, s3, 0
	s_mov_b32 s60, -2
	s_add_u32 s26, s2, 0xfffc0080
	s_addc_u32 s27, s3, -1
	s_cmp_eq_u32 s60, 12
	s_cselect_b32 s30, s23, s26
	s_cselect_b32 s31, s1, s27
	s_cselect_b32 s28, s55, s56
	s_cselect_b32 s29, s17, s57
	s_add_u32 s26, s30, 0x80
	s_addc_u32 s27, s31, 0
	s_add_i32 s61, 0, 0x10000
	s_add_i32 s66, 0, 0x14000
	v_add_u32_e32 v142, s61, v0
	v_add_u32_e32 v158, s66, v0
	ds_read_b128 v[98:101], v142
	ds_read_b128 v[118:121], v142 offset:1024
	ds_read_b128 v[138:141], v142 offset:2048
	ds_read_b128 v[142:145], v142 offset:3072
	ds_read_b128 v[146:149], v158
	ds_read_b128 v[150:153], v158 offset:1024
	ds_read_b128 v[154:157], v158 offset:2048
	ds_read_b128 v[158:161], v158 offset:3072
	s_mov_b64 s[64:65], s[2:3]
	v_mov_b32_e32 v177, v170
	ds_read_b128 v[162:165], v176
	ds_read_b128 v[166:169], v176 offset:1024
	ds_read_b128 v[178:181], v176 offset:2048
	ds_read_b128 v[182:185], v176 offset:3072
	ds_read_b128 v[186:189], v176 offset:4096
	ds_read_b128 v[190:193], v176 offset:5120
	ds_read_b128 v[194:197], v176 offset:6144
	ds_read_b128 v[198:201], v176 offset:7168
	s_add_i32 m0, s46, 0xc000
	s_nop 0
	global_load_lds_dwordx4 v177, s[64:65]
	v_mov_b32_e32 v177, v172
	s_add_i32 m0, s46, 0xe000
	s_nop 0
	global_load_lds_dwordx4 v177, s[64:65]
	s_waitcnt vmcnt(8)
	s_waitcnt lgkmcnt(0)
	s_barrier
	s_setprio 1
	s_waitcnt lgkmcnt(0)
	v_mfma_f32_16x16x32_bf16 v[134:137], v[98:101], v[162:165], 0
	v_mfma_f32_16x16x32_bf16 v[130:133], v[138:141], v[162:165], 0
	v_mfma_f32_16x16x32_bf16 v[114:117], v[98:101], v[178:181], 0
	v_mfma_f32_16x16x32_bf16 v[110:113], v[138:141], v[178:181], 0
	v_mfma_f32_16x16x32_bf16 v[94:97], v[98:101], v[186:189], 0
	v_mfma_f32_16x16x32_bf16 v[90:93], v[138:141], v[186:189], 0
	v_mfma_f32_16x16x32_bf16 v[78:81], v[98:101], v[194:197], 0
	v_mfma_f32_16x16x32_bf16 v[74:77], v[138:141], v[194:197], 0
	v_mfma_f32_16x16x32_bf16 v[134:137], v[118:121], v[166:169], v[134:137]
	v_mfma_f32_16x16x32_bf16 v[130:133], v[142:145], v[166:169], v[130:133]
	v_mfma_f32_16x16x32_bf16 v[114:117], v[118:121], v[182:185], v[114:117]
	v_mfma_f32_16x16x32_bf16 v[110:113], v[142:145], v[182:185], v[110:113]
	v_mfma_f32_16x16x32_bf16 v[94:97], v[118:121], v[190:193], v[94:97]
	v_mfma_f32_16x16x32_bf16 v[90:93], v[142:145], v[190:193], v[90:93]
	v_mfma_f32_16x16x32_bf16 v[78:81], v[118:121], v[198:201], v[78:81]
	v_mfma_f32_16x16x32_bf16 v[74:77], v[142:145], v[198:201], v[74:77]
	s_setprio 0
	s_setprio 1
	v_mfma_f32_16x16x32_bf16 v[126:129], v[146:149], v[162:165], 0
	v_mfma_f32_16x16x32_bf16 v[122:125], v[154:157], v[162:165], 0
	v_mfma_f32_16x16x32_bf16 v[106:109], v[146:149], v[178:181], 0
	v_mfma_f32_16x16x32_bf16 v[102:105], v[154:157], v[178:181], 0
	v_mfma_f32_16x16x32_bf16 v[86:89], v[146:149], v[186:189], 0
	v_mfma_f32_16x16x32_bf16 v[82:85], v[154:157], v[186:189], 0
	v_mfma_f32_16x16x32_bf16 v[70:73], v[146:149], v[194:197], 0
	v_mfma_f32_16x16x32_bf16 v[66:69], v[154:157], v[194:197], 0
	v_mfma_f32_16x16x32_bf16 v[126:129], v[150:153], v[166:169], v[126:129]
	v_mfma_f32_16x16x32_bf16 v[122:125], v[158:161], v[166:169], v[122:125]
	v_mfma_f32_16x16x32_bf16 v[106:109], v[150:153], v[182:185], v[106:109]
	v_mfma_f32_16x16x32_bf16 v[102:105], v[158:161], v[182:185], v[102:105]
	v_mfma_f32_16x16x32_bf16 v[86:89], v[150:153], v[190:193], v[86:89]
	v_mfma_f32_16x16x32_bf16 v[82:85], v[158:161], v[190:193], v[82:85]
	v_mfma_f32_16x16x32_bf16 v[70:73], v[150:153], v[198:201], v[70:73]
	v_mfma_f32_16x16x32_bf16 v[66:69], v[158:161], v[198:201], v[66:69]
	s_setprio 0
	s_barrier
	s_mov_b64 s[64:65], s[28:29]
	v_mov_b32_e32 v177, v171
	s_add_i32 s61, s61, s38
	ds_read_b128 v[162:165], v176 offset:16384
	ds_read_b128 v[166:169], v176 offset:17408
	ds_read_b128 v[178:181], v176 offset:18432
	ds_read_b128 v[182:185], v176 offset:19456
	ds_read_b128 v[186:189], v176 offset:20480
	ds_read_b128 v[190:193], v176 offset:21504
	ds_read_b128 v[194:197], v176 offset:22528
	ds_read_b128 v[198:201], v176 offset:23552
	s_mov_b32 m0, s61
	s_nop 0
	global_load_lds_dwordx4 v177, s[64:65]
	v_mov_b32_e32 v177, v173
	s_add_i32 m0, s61, 0x2000
	s_nop 0
	global_load_lds_dwordx4 v177, s[64:65]
	s_add_u32 s64, s28, 0x40000
	s_addc_u32 s65, s29, 0
	v_mov_b32_e32 v177, v171
	s_add_i32 s61, s66, s38
	s_mov_b32 m0, s61
	s_nop 0
	global_load_lds_dwordx4 v177, s[64:65]
	v_mov_b32_e32 v177, v173
	s_add_i32 m0, s61, 0x2000
	s_nop 0
	global_load_lds_dwordx4 v177, s[64:65]
	s_mov_b64 s[64:65], s[30:31]
	v_mov_b32_e32 v177, v170
	s_mov_b32 m0, s46
	s_nop 0
	global_load_lds_dwordx4 v177, s[64:65]
	v_mov_b32_e32 v177, v172
	s_mov_b32 m0, s47
	s_nop 0
	global_load_lds_dwordx4 v177, s[64:65]
	s_waitcnt vmcnt(8)
	s_waitcnt lgkmcnt(0)
	s_barrier
; #define PG8_STAGE(bufoff, gbase, voff) do { const char* _gb = (const char*)(gbase); asm volatile("" : "+s"(_gb)); _Pragma("unroll") for (int _i = 0; _i < 2; ++_i) { \
;         unsigned _vo = (voff)[_i]; asm volatile("" : "+v"(_vo));     \
;         __builtin_amdgcn_global_load_lds((const unsigned*)(_gb + _vo), (LAS unsigned*)(lds + (bufoff) + ldsw + _i * 8192), 16, 0, 0); } } while (0)
; #define PG8_LDA(dst, b, h) do { _Pragma("unroll") for (int m = 0; m < 4; ++m) _Pragma("unroll") for (int k = 0; k < 2; ++k) dst[m][k] = *(const LAS bf16x8*)(lds + PG8_SA(b, h) + aoff + m * 2048 + k * 1024); } while (0)
; #define PG8_LDB(dst, b, h) do { _Pragma("unroll") for (int n = 0; n < 2; ++n) _Pragma("unroll") for (int k = 0; k < 2; ++k) dst[n][k] = *(const LAS bf16x8*)(lds + PG8_SB(b, h) + boff + n * 2048 + k * 1024); } while (0)
; #define PG8_MMA(ai, bj, At, Bt) do { __builtin_amdgcn_s_setprio(1); _Pragma("unroll") for (int m = 0; m < 4; ++m) _Pragma("unroll") for (int n = 0; n < 2; ++n) _Pragma("unroll") for (int k = 0; k < 2; ++k) \
;         acc[ai][bj][m][n] = __builtin_amdgcn_mfma_f32_16x16x32_bf16(Bt[n][k], At[m][k], acc[ai][bj][m][n], 0, 0, 0); __builtin_amdgcn_s_setprio(0); } while (0)
; #define PG8_WAIT_V(n) asm volatile("s_waitcnt vmcnt(" #n ")" ::: "memory")
; #define PG8_WAIT_L(n) asm volatile("s_waitcnt lgkmcnt(" #n ")" ::: "memory")
; #define PG8_BAR __builtin_amdgcn_s_barrier()
; #define PG8_SCHED __builtin_amdgcn_sched_barrier(0)
; template <class Epi, class Sched>
; DI void gemm_phase(int wv, LAS unsigned char* lds, const Gemm g, const Sched& S, const Epi& E) {
;     ...
;             PG8_WAIT_V(8); PG8_WAIT_L(0); PG8_BAR; PG8_MMA(1, 0, At, B0); PG8_MMA(1, 1, At, B1); PG8_BAR; PG8_SCHED;
;             PG8_LDB(B0, 1, 0); PG8_LDB(B1, 1, 1); PG8_SCHED; PG8_LDA(At, 1, 0); PG8_STAGE(PG8_SA(0, 1), a2 + hstepA, voffA);
;             PG8_WAIT_V(8); PG8_WAIT_L(0); PG8_BAR; PG8_MMA(0, 0, At, B0); PG8_MMA(0, 1, At, B1); PG8_BAR; PG8_SCHED;
;             PG8_LDA(At, 1, 1); PG8_STAGE(PG8_SB(1, 0), b3, voffB); PG8_STAGE(PG8_SB(1, 1), b3 + hstepB, voffB); PG8_STAGE(PG8_SA(1, 0), a3, voffA);
	s_setprio 1
	s_waitcnt lgkmcnt(0)
	v_mfma_f32_16x16x32_bf16 v[62:65], v[98:101], v[162:165], 0
	v_mfma_f32_16x16x32_bf16 v[58:61], v[138:141], v[162:165], 0
	v_mfma_f32_16x16x32_bf16 v[46:49], v[98:101], v[178:181], 0
	v_mfma_f32_16x16x32_bf16 v[42:45], v[138:141], v[178:181], 0
	v_mfma_f32_16x16x32_bf16 v[30:33], v[98:101], v[186:189], 0
	v_mfma_f32_16x16x32_bf16 v[26:29], v[138:141], v[186:189], 0
	v_mfma_f32_16x16x32_bf16 v[14:17], v[98:101], v[194:197], 0
	v_mfma_f32_16x16x32_bf16 v[10:13], v[138:141], v[194:197], 0
	v_mfma_f32_16x16x32_bf16 v[62:65], v[118:121], v[166:169], v[62:65]
	v_mfma_f32_16x16x32_bf16 v[58:61], v[142:145], v[166:169], v[58:61]
	v_mfma_f32_16x16x32_bf16 v[46:49], v[118:121], v[182:185], v[46:49]
	v_mfma_f32_16x16x32_bf16 v[42:45], v[142:145], v[182:185], v[42:45]
	v_mfma_f32_16x16x32_bf16 v[30:33], v[118:121], v[190:193], v[30:33]
	v_mfma_f32_16x16x32_bf16 v[26:29], v[142:145], v[190:193], v[26:29]
	v_mfma_f32_16x16x32_bf16 v[14:17], v[118:121], v[198:201], v[14:17]
	v_mfma_f32_16x16x32_bf16 v[10:13], v[142:145], v[198:201], v[10:13]
	s_setprio 0
	s_setprio 1
	v_mfma_f32_16x16x32_bf16 v[54:57], v[146:149], v[162:165], 0
	v_mfma_f32_16x16x32_bf16 v[50:53], v[154:157], v[162:165], 0
	v_mfma_f32_16x16x32_bf16 v[38:41], v[146:149], v[178:181], 0
	v_mfma_f32_16x16x32_bf16 v[34:37], v[154:157], v[178:181], 0
	v_mfma_f32_16x16x32_bf16 v[22:25], v[146:149], v[186:189], 0
	v_mfma_f32_16x16x32_bf16 v[18:21], v[154:157], v[186:189], 0
	v_mfma_f32_16x16x32_bf16 v[6:9], v[146:149], v[194:197], 0
	v_mfma_f32_16x16x32_bf16 v[2:5], v[154:157], v[194:197], 0
	v_mfma_f32_16x16x32_bf16 v[54:57], v[150:153], v[166:169], v[54:57]
	v_mfma_f32_16x16x32_bf16 v[50:53], v[158:161], v[166:169], v[50:53]
	v_mfma_f32_16x16x32_bf16 v[38:41], v[150:153], v[182:185], v[38:41]
	v_mfma_f32_16x16x32_bf16 v[34:37], v[158:161], v[182:185], v[34:37]
	v_mfma_f32_16x16x32_bf16 v[22:25], v[150:153], v[190:193], v[22:25]
	v_mfma_f32_16x16x32_bf16 v[18:21], v[158:161], v[190:193], v[18:21]
	v_mfma_f32_16x16x32_bf16 v[6:9], v[150:153], v[198:201], v[6:9]
	v_mfma_f32_16x16x32_bf16 v[2:5], v[158:161], v[198:201], v[2:5]
	s_setprio 0
	s_barrier
	s_add_i32 s61, 0, 0x18000
	s_add_i32 s64, 0, 0x1c000
	v_add_u32_e32 v142, s61, v0
	v_add_u32_e32 v158, s64, v0
	ds_read_b128 v[98:101], v142
	ds_read_b128 v[118:121], v142 offset:1024
	ds_read_b128 v[138:141], v142 offset:2048
	ds_read_b128 v[142:145], v142 offset:3072
	ds_read_b128 v[146:149], v158
	ds_read_b128 v[150:153], v158 offset:1024
	ds_read_b128 v[154:157], v158 offset:2048
	ds_read_b128 v[158:161], v158 offset:3072
	s_add_u32 s30, s30, 0x40000
	s_addc_u32 s31, s31, 0
	v_mov_b32_e32 v177, v170
	s_mov_b32 m0, s48
	ds_read_b128 v[162:165], v176 offset:32768
	ds_read_b128 v[166:169], v176 offset:33792
	ds_read_b128 v[178:181], v176 offset:34816
	ds_read_b128 v[182:185], v176 offset:35840
	ds_read_b128 v[186:189], v176 offset:36864
	ds_read_b128 v[190:193], v176 offset:37888
	ds_read_b128 v[194:197], v176 offset:38912
	ds_read_b128 v[198:201], v176 offset:39936
	s_nop 0
	global_load_lds_dwordx4 v177, s[30:31]
	v_mov_b32_e32 v177, v172
	s_mov_b32 m0, s49
	s_nop 0
	global_load_lds_dwordx4 v177, s[30:31]
	s_waitcnt vmcnt(8)
	s_waitcnt lgkmcnt(0)
	s_barrier
	s_setprio 1
	s_waitcnt lgkmcnt(0)
	v_mfma_f32_16x16x32_bf16 v[134:137], v[98:101], v[162:165], v[134:137]
	v_mfma_f32_16x16x32_bf16 v[130:133], v[138:141], v[162:165], v[130:133]
	v_mfma_f32_16x16x32_bf16 v[114:117], v[98:101], v[178:181], v[114:117]
	v_mfma_f32_16x16x32_bf16 v[110:113], v[138:141], v[178:181], v[110:113]
	v_mfma_f32_16x16x32_bf16 v[94:97], v[98:101], v[186:189], v[94:97]
	v_mfma_f32_16x16x32_bf16 v[90:93], v[138:141], v[186:189], v[90:93]
	v_mfma_f32_16x16x32_bf16 v[78:81], v[98:101], v[194:197], v[78:81]
	v_mfma_f32_16x16x32_bf16 v[74:77], v[138:141], v[194:197], v[74:77]
	v_mfma_f32_16x16x32_bf16 v[134:137], v[118:121], v[166:169], v[134:137]
	v_mfma_f32_16x16x32_bf16 v[130:133], v[142:145], v[166:169], v[130:133]
	v_mfma_f32_16x16x32_bf16 v[114:117], v[118:121], v[182:185], v[114:117]
	v_mfma_f32_16x16x32_bf16 v[110:113], v[142:145], v[182:185], v[110:113]
	v_mfma_f32_16x16x32_bf16 v[94:97], v[118:121], v[190:193], v[94:97]
	v_mfma_f32_16x16x32_bf16 v[90:93], v[142:145], v[190:193], v[90:93]
	v_mfma_f32_16x16x32_bf16 v[78:81], v[118:121], v[198:201], v[78:81]
	v_mfma_f32_16x16x32_bf16 v[74:77], v[142:145], v[198:201], v[74:77]
	s_setprio 0
	s_setprio 1
	v_mfma_f32_16x16x32_bf16 v[126:129], v[146:149], v[162:165], v[126:129]
	v_mfma_f32_16x16x32_bf16 v[122:125], v[154:157], v[162:165], v[122:125]
	v_mfma_f32_16x16x32_bf16 v[106:109], v[146:149], v[178:181], v[106:109]
	v_mfma_f32_16x16x32_bf16 v[102:105], v[154:157], v[178:181], v[102:105]
	v_mfma_f32_16x16x32_bf16 v[86:89], v[146:149], v[186:189], v[86:89]
	v_mfma_f32_16x16x32_bf16 v[82:85], v[154:157], v[186:189], v[82:85]
	v_mfma_f32_16x16x32_bf16 v[70:73], v[146:149], v[194:197], v[70:73]
	v_mfma_f32_16x16x32_bf16 v[66:69], v[154:157], v[194:197], v[66:69]
	v_mfma_f32_16x16x32_bf16 v[126:129], v[150:153], v[166:169], v[126:129]
	v_mfma_f32_16x16x32_bf16 v[122:125], v[158:161], v[166:169], v[122:125]
	v_mfma_f32_16x16x32_bf16 v[106:109], v[150:153], v[182:185], v[106:109]
	v_mfma_f32_16x16x32_bf16 v[102:105], v[158:161], v[182:185], v[102:105]
	v_mfma_f32_16x16x32_bf16 v[86:89], v[150:153], v[190:193], v[86:89]
	v_mfma_f32_16x16x32_bf16 v[82:85], v[158:161], v[190:193], v[82:85]
	v_mfma_f32_16x16x32_bf16 v[70:73], v[150:153], v[198:201], v[70:73]
	v_mfma_f32_16x16x32_bf16 v[66:69], v[158:161], v[198:201], v[66:69]
	s_setprio 0
	s_barrier
; #define PG8_STAGE(bufoff, gbase, voff) do { const char* _gb = (const char*)(gbase); asm volatile("" : "+s"(_gb)); _Pragma("unroll") for (int _i = 0; _i < 2; ++_i) { \
;         unsigned _vo = (voff)[_i]; asm volatile("" : "+v"(_vo));     \
;         __builtin_amdgcn_global_load_lds((const unsigned*)(_gb + _vo), (LAS unsigned*)(lds + (bufoff) + ldsw + _i * 8192), 16, 0, 0); } } while (0)
; #define PG8_LDA(dst, b, h) do { _Pragma("unroll") for (int m = 0; m < 4; ++m) _Pragma("unroll") for (int k = 0; k < 2; ++k) dst[m][k] = *(const LAS bf16x8*)(lds + PG8_SA(b, h) + aoff + m * 2048 + k * 1024); } while (0)
; #define PG8_MMA(ai, bj, At, Bt) do { __builtin_amdgcn_s_setprio(1); _Pragma("unroll") for (int m = 0; m < 4; ++m) _Pragma("unroll") for (int n = 0; n < 2; ++n) _Pragma("unroll") for (int k = 0; k < 2; ++k) \
;         acc[ai][bj][m][n] = __builtin_amdgcn_mfma_f32_16x16x32_bf16(Bt[n][k], At[m][k], acc[ai][bj][m][n], 0, 0, 0); __builtin_amdgcn_s_setprio(0); } while (0)
; #define PG8_WAIT_V(n) asm volatile("s_waitcnt vmcnt(" #n ")" ::: "memory")
; #define PG8_WAIT_L(n) asm volatile("s_waitcnt lgkmcnt(" #n ")" ::: "memory")
; #define PG8_BAR __builtin_amdgcn_s_barrier()
; #define PG8_SCHED __builtin_amdgcn_sched_barrier(0)
; template <class Epi, class Sched>
; DI void gemm_phase(int wv, LAS unsigned char* lds, const Gemm g, const Sched& S, const Epi& E) {
;     ...
;             PG8_LDA(At, 1, 1); PG8_STAGE(PG8_SB(1, 0), b3, voffB); PG8_STAGE(PG8_SB(1, 1), b3 + hstepB, voffB); PG8_STAGE(PG8_SA(1, 0), a3, voffA);
;             PG8_WAIT_V(8); PG8_WAIT_L(0); PG8_BAR; PG8_MMA(1, 0, At, B0); PG8_MMA(1, 1, At, B1); PG8_BAR; PG8_SCHED;
	s_add_u32 s30, s28, 0x80
	s_addc_u32 s31, s29, 0
	v_mov_b32_e32 v177, v171
	s_add_i32 s61, s61, s38
	ds_read_b128 v[162:165], v176 offset:49152
	ds_read_b128 v[166:169], v176 offset:50176
	ds_read_b128 v[178:181], v176 offset:51200
	ds_read_b128 v[182:185], v176 offset:52224
	ds_read_b128 v[186:189], v176 offset:53248
	ds_read_b128 v[190:193], v176 offset:54272
	ds_read_b128 v[194:197], v176 offset:55296
	ds_read_b128 v[198:201], v176 offset:56320
	s_mov_b32 m0, s61
	s_nop 0
	global_load_lds_dwordx4 v177, s[30:31]
	v_mov_b32_e32 v177, v173
	s_add_i32 m0, s61, 0x2000
	s_add_u32 s28, s28, 0x40080
	global_load_lds_dwordx4 v177, s[30:31]
	s_addc_u32 s29, s29, 0
	v_mov_b32_e32 v177, v171
	s_add_i32 s30, s64, s38
	s_mov_b32 m0, s30
	s_nop 0
	global_load_lds_dwordx4 v177, s[28:29]
	v_mov_b32_e32 v177, v173
	s_add_i32 m0, s30, 0x2000
	s_nop 0
	global_load_lds_dwordx4 v177, s[28:29]
	v_mov_b32_e32 v177, v170
	s_mov_b32 m0, s50
	s_nop 0
	global_load_lds_dwordx4 v177, s[26:27]
	v_mov_b32_e32 v177, v172
	s_mov_b32 m0, s51
	s_nop 0
	global_load_lds_dwordx4 v177, s[26:27]
	s_waitcnt vmcnt(8)
	s_waitcnt lgkmcnt(0)
	s_barrier
	s_setprio 1
	s_waitcnt lgkmcnt(0)
	v_mfma_f32_16x16x32_bf16 v[62:65], v[98:101], v[162:165], v[62:65]
	v_mfma_f32_16x16x32_bf16 v[58:61], v[138:141], v[162:165], v[58:61]
	v_mfma_f32_16x16x32_bf16 v[46:49], v[98:101], v[178:181], v[46:49]
	v_mfma_f32_16x16x32_bf16 v[42:45], v[138:141], v[178:181], v[42:45]
	v_mfma_f32_16x16x32_bf16 v[30:33], v[98:101], v[186:189], v[30:33]
	v_mfma_f32_16x16x32_bf16 v[26:29], v[138:141], v[186:189], v[26:29]
	v_mfma_f32_16x16x32_bf16 v[14:17], v[98:101], v[194:197], v[14:17]
	v_mfma_f32_16x16x32_bf16 v[10:13], v[138:141], v[194:197], v[10:13]
	v_mfma_f32_16x16x32_bf16 v[62:65], v[118:121], v[166:169], v[62:65]
	v_mfma_f32_16x16x32_bf16 v[58:61], v[142:145], v[166:169], v[58:61]
	v_mfma_f32_16x16x32_bf16 v[46:49], v[118:121], v[182:185], v[46:49]
	v_mfma_f32_16x16x32_bf16 v[42:45], v[142:145], v[182:185], v[42:45]
	v_mfma_f32_16x16x32_bf16 v[30:33], v[118:121], v[190:193], v[30:33]
	v_mfma_f32_16x16x32_bf16 v[26:29], v[142:145], v[190:193], v[26:29]
	v_mfma_f32_16x16x32_bf16 v[14:17], v[118:121], v[198:201], v[14:17]
	v_mfma_f32_16x16x32_bf16 v[10:13], v[142:145], v[198:201], v[10:13]
	s_setprio 0
	s_setprio 1
	v_mfma_f32_16x16x32_bf16 v[54:57], v[146:149], v[162:165], v[54:57]
	v_mfma_f32_16x16x32_bf16 v[50:53], v[154:157], v[162:165], v[50:53]
	v_mfma_f32_16x16x32_bf16 v[38:41], v[146:149], v[178:181], v[38:41]
	v_mfma_f32_16x16x32_bf16 v[34:37], v[154:157], v[178:181], v[34:37]
	v_mfma_f32_16x16x32_bf16 v[22:25], v[146:149], v[186:189], v[22:25]
	v_mfma_f32_16x16x32_bf16 v[18:21], v[154:157], v[186:189], v[18:21]
	v_mfma_f32_16x16x32_bf16 v[6:9], v[146:149], v[194:197], v[6:9]
	v_mfma_f32_16x16x32_bf16 v[2:5], v[154:157], v[194:197], v[2:5]
	v_mfma_f32_16x16x32_bf16 v[54:57], v[150:153], v[166:169], v[54:57]
	v_mfma_f32_16x16x32_bf16 v[50:53], v[158:161], v[166:169], v[50:53]
	v_mfma_f32_16x16x32_bf16 v[38:41], v[150:153], v[182:185], v[38:41]
	v_mfma_f32_16x16x32_bf16 v[34:37], v[158:161], v[182:185], v[34:37]
	v_mfma_f32_16x16x32_bf16 v[22:25], v[150:153], v[190:193], v[22:25]
	v_mfma_f32_16x16x32_bf16 v[18:21], v[158:161], v[190:193], v[18:21]
	v_mfma_f32_16x16x32_bf16 v[6:9], v[150:153], v[198:201], v[6:9]
	v_mfma_f32_16x16x32_bf16 v[2:5], v[158:161], v[198:201], v[2:5]
	s_setprio 0
	s_barrier
	s_add_i32 s60, s60, 2
	s_add_u32 s56, s56, 0x100
	s_addc_u32 s57, s57, 0
	s_add_u32 s2, s2, 0x100
	s_addc_u32 s3, s3, 0
	s_cmp_gt_u32 s60, 13

; #define PG8_STAGE(bufoff, gbase, voff) do { const char* _gb = (const char*)(gbase); asm volatile("" : "+s"(_gb)); _Pragma("unroll") for (int _i = 0; _i < 2; ++_i) { \
;         unsigned _vo = (voff)[_i]; asm volatile("" : "+v"(_vo));     \
;         __builtin_amdgcn_global_load_lds((const unsigned*)(_gb + _vo), (LAS unsigned*)(lds + (bufoff) + ldsw + _i * 8192), 16, 0, 0); } } while (0)
; #define PG8_LDA(dst, b, h) do { _Pragma("unroll") for (int m = 0; m < 4; ++m) _Pragma("unroll") for (int k = 0; k < 2; ++k) dst[m][k] = *(const LAS bf16x8*)(lds + PG8_SA(b, h) + aoff + m * 2048 + k * 1024); } while (0)
; template <class Epi, class Sched>
; DI void gemm_phase(int wv, LAS unsigned char* lds, const Gemm g, const Sched& S, const Epi& E) {
;     ...
;     const char* cA = (const char*)g.A + (size_t)cur.pm * tstepA; const char* cB = (const char*)g.Bt + (size_t)cur.pn * tstepB;
;     float rsn[2][4];
;     if constexpr (epi_prefetch<Epi>::value) E.pre(cur, wr, wc, fr, fq, rsn);
;     PG8_STAGE(PG8_SB(0, 0), cB, voffB); PG8_STAGE(PG8_SB(0, 1), cB + hstepB, voffB); PG8_STAGE(PG8_SA(0, 0), cA, voffA); PG8_STAGE(PG8_SA(0, 1), cA + hstepA, voffA);
;     if (wr == 1) PG8_BAR;
;     PG8_WAIT_V(2); PG8_BAR;
;     PG8_STAGE(PG8_SB(1, 0), cB + kstep, voffB); PG8_STAGE(PG8_SA(1, 0), cA + kstep, voffA); PG8_STAGE(PG8_SB(1, 1), cB + hstepB + kstep, voffB);
;     PG8_WAIT_V(6); PG8_BAR;
;     for (;;) {
;         const bool has_next = S.next(ui + 1, nxt);
;         const char* nA = has_next ? (const char*)g.A + (size_t)nxt.pm * tstepA : cA; const char* nB = has_next ? (const char*)g.Bt + (size_t)nxt.pn * tstepB : cB;
; #pragma nounroll
;         for (int t = 0; t < nt; t += 2) {
;             const bool last = (t == nt - 2);
;             const char* a1 = cA + (size_t)(t + 1) * kstep;
;             const char* a2 = last ? nA : cA + (size_t)(t + 2) * kstep; const char* b2 = last ? nB : cB + (size_t)(t + 2) * kstep;
;             const char* a3 = a2 + kstep; const char* b3 = b2 + kstep;
;             PG8_LDB(B0, 0, 0); PG8_LDB(B1, 0, 1); PG8_SCHED; PG8_LDA(At, 0, 0); PG8_STAGE(PG8_SA(1, 1), a1 + hstepA, voffA);
;             PG8_WAIT_V(8); PG8_WAIT_L(0); PG8_BAR; PG8_MMA(0, 0, At, B0); PG8_MMA(0, 1, At, B1); PG8_BAR; PG8_SCHED;
;             PG8_LDA(At, 0, 1); PG8_STAGE(PG8_SB(0, 0), b2, voffB); PG8_STAGE(PG8_SB(0, 1), b2 + hstepB, voffB); PG8_STAGE(PG8_SA(0, 0), a2, voffA);
.LBB0_1886:
	s_ashr_i32 s23, s22, 31
	s_lshl_b64 s[28:29], s[22:23], 19
	s_add_u32 s28, s46, s28
	s_addc_u32 s29, s47, s29
	s_and_b64 s[30:31], s[26:27], exec
	s_cselect_b32 s1, s29, s7
	s_cselect_b32 s3, s28, s6
	s_ashr_i32 s25, s24, 31
	s_lshl_b64 s[30:31], s[24:25], 19
	s_add_u32 s30, s50, s30
	s_addc_u32 s31, s51, s31
	s_and_b64 s[34:35], s[26:27], exec
	s_cselect_b32 s23, s31, s5
	s_cselect_b32 s25, s30, s4
	s_add_u32 s38, s4, 0x100
	s_addc_u32 s39, s5, 0
	s_add_u32 s4, s6, 0x40080
	s_addc_u32 s5, s7, 0
	s_mov_b32 s44, -2
	s_waitcnt vmcnt(0)
	s_add_u32 s6, s4, 0xfffc0080
	s_addc_u32 s7, s5, -1
	s_cmp_eq_u32 s44, 12
	s_cselect_b32 s36, s3, s6
	s_cselect_b32 s37, s1, s7
	s_cselect_b32 s34, s25, s38
	s_cselect_b32 s35, s23, s39
	s_add_u32 s6, s36, 0x80
	s_addc_u32 s7, s37, 0
	s_add_i32 s45, 0, 0x10000
	v_add_u32_e32 v0, s45, v176
	s_add_i32 s70, 0, 0x14000
	ds_read_b128 v[130:133], v0
	ds_read_b128 v[134:137], v0 offset:1024
	ds_read_b128 v[138:141], v0 offset:2048
	ds_read_b128 v[142:145], v0 offset:3072
	v_add_u32_e32 v0, s70, v176
	ds_read_b128 v[146:149], v0
	ds_read_b128 v[150:153], v0 offset:1024
	ds_read_b128 v[154:157], v0 offset:2048
	ds_read_b128 v[158:161], v0 offset:3072
	s_mov_b64 s[48:49], s[4:5]
	v_mov_b32_e32 v0, v172
	ds_read_b128 v[162:165], v177
	ds_read_b128 v[166:169], v177 offset:1024
	ds_read_b128 v[178:181], v177 offset:2048
	ds_read_b128 v[182:185], v177 offset:3072
	ds_read_b128 v[186:189], v177 offset:4096
	ds_read_b128 v[190:193], v177 offset:5120
	ds_read_b128 v[194:197], v177 offset:6144
	ds_read_b128 v[198:201], v177 offset:7168
	s_add_i32 m0, s55, 0xc000
	s_nop 0
	global_load_lds_dwordx4 v0, s[48:49]
	v_mov_b32_e32 v0, v174
	s_add_i32 m0, s55, 0xe000
	s_nop 0
	global_load_lds_dwordx4 v0, s[48:49]
	s_waitcnt vmcnt(8)
	s_waitcnt lgkmcnt(0)
	s_barrier
	s_setprio 1
	s_waitcnt lgkmcnt(0)
	v_mfma_f32_16x16x32_bf16 v[126:129], v[130:133], v[162:165], 0
	v_mfma_f32_16x16x32_bf16 v[122:125], v[138:141], v[162:165], 0
	v_mfma_f32_16x16x32_bf16 v[110:113], v[130:133], v[178:181], 0
	v_mfma_f32_16x16x32_bf16 v[106:109], v[138:141], v[178:181], 0
	v_mfma_f32_16x16x32_bf16 v[94:97], v[130:133], v[186:189], 0
	v_mfma_f32_16x16x32_bf16 v[90:93], v[138:141], v[186:189], 0
	v_mfma_f32_16x16x32_bf16 v[78:81], v[130:133], v[194:197], 0
	v_mfma_f32_16x16x32_bf16 v[74:77], v[138:141], v[194:197], 0
	v_mfma_f32_16x16x32_bf16 v[126:129], v[134:137], v[166:169], v[126:129]
	v_mfma_f32_16x16x32_bf16 v[122:125], v[142:145], v[166:169], v[122:125]
	v_mfma_f32_16x16x32_bf16 v[110:113], v[134:137], v[182:185], v[110:113]
	v_mfma_f32_16x16x32_bf16 v[106:109], v[142:145], v[182:185], v[106:109]
	v_mfma_f32_16x16x32_bf16 v[94:97], v[134:137], v[190:193], v[94:97]
	v_mfma_f32_16x16x32_bf16 v[90:93], v[142:145], v[190:193], v[90:93]
	v_mfma_f32_16x16x32_bf16 v[78:81], v[134:137], v[198:201], v[78:81]
	v_mfma_f32_16x16x32_bf16 v[74:77], v[142:145], v[198:201], v[74:77]
	s_setprio 0
	s_setprio 1
	v_mfma_f32_16x16x32_bf16 v[118:121], v[146:149], v[162:165], 0
	v_mfma_f32_16x16x32_bf16 v[114:117], v[154:157], v[162:165], 0
	v_mfma_f32_16x16x32_bf16 v[102:105], v[146:149], v[178:181], 0
	v_mfma_f32_16x16x32_bf16 v[98:101], v[154:157], v[178:181], 0
	v_mfma_f32_16x16x32_bf16 v[86:89], v[146:149], v[186:189], 0
	v_mfma_f32_16x16x32_bf16 v[82:85], v[154:157], v[186:189], 0
	v_mfma_f32_16x16x32_bf16 v[70:73], v[146:149], v[194:197], 0
	v_mfma_f32_16x16x32_bf16 v[66:69], v[154:157], v[194:197], 0
	v_mfma_f32_16x16x32_bf16 v[118:121], v[150:153], v[166:169], v[118:121]
	v_mfma_f32_16x16x32_bf16 v[114:117], v[158:161], v[166:169], v[114:117]
	v_mfma_f32_16x16x32_bf16 v[102:105], v[150:153], v[182:185], v[102:105]
	v_mfma_f32_16x16x32_bf16 v[98:101], v[158:161], v[182:185], v[98:101]
	v_mfma_f32_16x16x32_bf16 v[86:89], v[150:153], v[190:193], v[86:89]
	v_mfma_f32_16x16x32_bf16 v[82:85], v[158:161], v[190:193], v[82:85]
	v_mfma_f32_16x16x32_bf16 v[70:73], v[150:153], v[198:201], v[70:73]
	v_mfma_f32_16x16x32_bf16 v[66:69], v[158:161], v[198:201], v[66:69]
	s_setprio 0
	s_barrier
	s_mov_b64 s[48:49], s[34:35]
	v_mov_b32_e32 v0, v173
	s_add_i32 s45, s45, s54
	ds_read_b128 v[162:165], v177 offset:16384
	ds_read_b128 v[166:169], v177 offset:17408
	ds_read_b128 v[178:181], v177 offset:18432
	ds_read_b128 v[182:185], v177 offset:19456
	ds_read_b128 v[186:189], v177 offset:20480
	ds_read_b128 v[190:193], v177 offset:21504
	ds_read_b128 v[194:197], v177 offset:22528
	ds_read_b128 v[198:201], v177 offset:23552
	s_mov_b32 m0, s45
	s_nop 0
	global_load_lds_dwordx4 v0, s[48:49]
	v_mov_b32_e32 v0, v175
	s_add_i32 m0, s45, 0x2000
	s_nop 0
	global_load_lds_dwordx4 v0, s[48:49]
	s_add_u32 s48, s34, 0x40000
	s_addc_u32 s49, s35, 0
	v_mov_b32_e32 v0, v173
	s_add_i32 s45, s70, s54
	s_mov_b32 m0, s45
	s_nop 0
	global_load_lds_dwordx4 v0, s[48:49]
	v_mov_b32_e32 v0, v175
	s_add_i32 m0, s45, 0x2000
	s_nop 0
	global_load_lds_dwordx4 v0, s[48:49]
	s_mov_b64 s[48:49], s[36:37]
	v_mov_b32_e32 v0, v172
	s_mov_b32 m0, s55
	s_nop 0
	global_load_lds_dwordx4 v0, s[48:49]
	v_mov_b32_e32 v0, v174
	s_mov_b32 m0, s56
	s_nop 0
	global_load_lds_dwordx4 v0, s[48:49]
	s_waitcnt vmcnt(8)
	s_waitcnt lgkmcnt(0)
	s_barrier
; #define PG8_STAGE(bufoff, gbase, voff) do { const char* _gb = (const char*)(gbase); asm volatile("" : "+s"(_gb)); _Pragma("unroll") for (int _i = 0; _i < 2; ++_i) { \
;         unsigned _vo = (voff)[_i]; asm volatile("" : "+v"(_vo));     \
;         __builtin_amdgcn_global_load_lds((const unsigned*)(_gb + _vo), (LAS unsigned*)(lds + (bufoff) + ldsw + _i * 8192), 16, 0, 0); } } while (0)
; #define PG8_LDA(dst, b, h) do { _Pragma("unroll") for (int m = 0; m < 4; ++m) _Pragma("unroll") for (int k = 0; k < 2; ++k) dst[m][k] = *(const LAS bf16x8*)(lds + PG8_SA(b, h) + aoff + m * 2048 + k * 1024); } while (0)
; #define PG8_LDB(dst, b, h) do { _Pragma("unroll") for (int n = 0; n < 2; ++n) _Pragma("unroll") for (int k = 0; k < 2; ++k) dst[n][k] = *(const LAS bf16x8*)(lds + PG8_SB(b, h) + boff + n * 2048 + k * 1024); } while (0)
; #define PG8_MMA(ai, bj, At, Bt) do { __builtin_amdgcn_s_setprio(1); _Pragma("unroll") for (int m = 0; m < 4; ++m) _Pragma("unroll") for (int n = 0; n < 2; ++n) _Pragma("unroll") for (int k = 0; k < 2; ++k) \
;         acc[ai][bj][m][n] = __builtin_amdgcn_mfma_f32_16x16x32_bf16(Bt[n][k], At[m][k], acc[ai][bj][m][n], 0, 0, 0); __builtin_amdgcn_s_setprio(0); } while (0)
; #define PG8_WAIT_V(n) asm volatile("s_waitcnt vmcnt(" #n ")" ::: "memory")
; #define PG8_WAIT_L(n) asm volatile("s_waitcnt lgkmcnt(" #n ")" ::: "memory")
; #define PG8_BAR __builtin_amdgcn_s_barrier()
; #define PG8_SCHED __builtin_amdgcn_sched_barrier(0)
; template <class Epi, class Sched>
; DI void gemm_phase(int wv, LAS unsigned char* lds, const Gemm g, const Sched& S, const Epi& E) {
;     ...
;             PG8_WAIT_V(8); PG8_WAIT_L(0); PG8_BAR; PG8_MMA(1, 0, At, B0); PG8_MMA(1, 1, At, B1); PG8_BAR; PG8_SCHED;
;             PG8_LDB(B0, 1, 0); PG8_LDB(B1, 1, 1); PG8_SCHED; PG8_LDA(At, 1, 0); PG8_STAGE(PG8_SA(0, 1), a2 + hstepA, voffA);
;             PG8_WAIT_V(8); PG8_WAIT_L(0); PG8_BAR; PG8_MMA(0, 0, At, B0); PG8_MMA(0, 1, At, B1); PG8_BAR; PG8_SCHED;
;             PG8_LDA(At, 1, 1); PG8_STAGE(PG8_SB(1, 0), b3, voffB); PG8_STAGE(PG8_SB(1, 1), b3 + hstepB, voffB); PG8_STAGE(PG8_SA(1, 0), a3, voffA);
	s_setprio 1
	s_waitcnt lgkmcnt(0)
	v_mfma_f32_16x16x32_bf16 v[62:65], v[130:133], v[162:165], 0
	v_mfma_f32_16x16x32_bf16 v[58:61], v[138:141], v[162:165], 0
	v_mfma_f32_16x16x32_bf16 v[46:49], v[130:133], v[178:181], 0
	v_mfma_f32_16x16x32_bf16 v[42:45], v[138:141], v[178:181], 0
	v_mfma_f32_16x16x32_bf16 v[30:33], v[130:133], v[186:189], 0
	v_mfma_f32_16x16x32_bf16 v[26:29], v[138:141], v[186:189], 0
	v_mfma_f32_16x16x32_bf16 v[14:17], v[130:133], v[194:197], 0
	v_mfma_f32_16x16x32_bf16 v[10:13], v[138:141], v[194:197], 0
	v_mfma_f32_16x16x32_bf16 v[62:65], v[134:137], v[166:169], v[62:65]
	v_mfma_f32_16x16x32_bf16 v[58:61], v[142:145], v[166:169], v[58:61]
	v_mfma_f32_16x16x32_bf16 v[46:49], v[134:137], v[182:185], v[46:49]
	v_mfma_f32_16x16x32_bf16 v[42:45], v[142:145], v[182:185], v[42:45]
	v_mfma_f32_16x16x32_bf16 v[30:33], v[134:137], v[190:193], v[30:33]
	v_mfma_f32_16x16x32_bf16 v[26:29], v[142:145], v[190:193], v[26:29]
	v_mfma_f32_16x16x32_bf16 v[14:17], v[134:137], v[198:201], v[14:17]
	v_mfma_f32_16x16x32_bf16 v[10:13], v[142:145], v[198:201], v[10:13]
	s_setprio 0
	s_setprio 1
	v_mfma_f32_16x16x32_bf16 v[54:57], v[146:149], v[162:165], 0
	v_mfma_f32_16x16x32_bf16 v[50:53], v[154:157], v[162:165], 0
	v_mfma_f32_16x16x32_bf16 v[38:41], v[146:149], v[178:181], 0
	v_mfma_f32_16x16x32_bf16 v[34:37], v[154:157], v[178:181], 0
	v_mfma_f32_16x16x32_bf16 v[22:25], v[146:149], v[186:189], 0
	v_mfma_f32_16x16x32_bf16 v[18:21], v[154:157], v[186:189], 0
	v_mfma_f32_16x16x32_bf16 v[6:9], v[146:149], v[194:197], 0
	v_mfma_f32_16x16x32_bf16 v[2:5], v[154:157], v[194:197], 0
	v_mfma_f32_16x16x32_bf16 v[54:57], v[150:153], v[166:169], v[54:57]
	v_mfma_f32_16x16x32_bf16 v[50:53], v[158:161], v[166:169], v[50:53]
	v_mfma_f32_16x16x32_bf16 v[38:41], v[150:153], v[182:185], v[38:41]
	v_mfma_f32_16x16x32_bf16 v[34:37], v[158:161], v[182:185], v[34:37]
	v_mfma_f32_16x16x32_bf16 v[22:25], v[150:153], v[190:193], v[22:25]
	v_mfma_f32_16x16x32_bf16 v[18:21], v[158:161], v[190:193], v[18:21]
	v_mfma_f32_16x16x32_bf16 v[6:9], v[150:153], v[198:201], v[6:9]
	v_mfma_f32_16x16x32_bf16 v[2:5], v[158:161], v[198:201], v[2:5]
	s_setprio 0
	s_barrier
	s_add_i32 s45, 0, 0x18000
	v_add_u32_e32 v0, s45, v176
	s_add_i32 s48, 0, 0x1c000
	ds_read_b128 v[130:133], v0
	ds_read_b128 v[134:137], v0 offset:1024
	ds_read_b128 v[138:141], v0 offset:2048
	ds_read_b128 v[142:145], v0 offset:3072
	v_add_u32_e32 v0, s48, v176
	ds_read_b128 v[146:149], v0
	ds_read_b128 v[150:153], v0 offset:1024
	ds_read_b128 v[154:157], v0 offset:2048
	ds_read_b128 v[158:161], v0 offset:3072
	s_add_u32 s36, s36, 0x40000
	s_addc_u32 s37, s37, 0
	v_mov_b32_e32 v0, v172
	s_mov_b32 m0, s57
	ds_read_b128 v[162:165], v177 offset:32768
	ds_read_b128 v[166:169], v177 offset:33792
	ds_read_b128 v[178:181], v177 offset:34816
	ds_read_b128 v[182:185], v177 offset:35840
	ds_read_b128 v[186:189], v177 offset:36864
	ds_read_b128 v[190:193], v177 offset:37888
	ds_read_b128 v[194:197], v177 offset:38912
	ds_read_b128 v[198:201], v177 offset:39936
	s_nop 0
	global_load_lds_dwordx4 v0, s[36:37]
	v_mov_b32_e32 v0, v174
	s_mov_b32 m0, s60
	s_nop 0
	global_load_lds_dwordx4 v0, s[36:37]
	s_waitcnt vmcnt(8)
	s_waitcnt lgkmcnt(0)
	s_barrier
	s_setprio 1
	s_waitcnt lgkmcnt(0)
	v_mfma_f32_16x16x32_bf16 v[126:129], v[130:133], v[162:165], v[126:129]
	v_mfma_f32_16x16x32_bf16 v[122:125], v[138:141], v[162:165], v[122:125]
	v_mfma_f32_16x16x32_bf16 v[110:113], v[130:133], v[178:181], v[110:113]
	v_mfma_f32_16x16x32_bf16 v[106:109], v[138:141], v[178:181], v[106:109]
	v_mfma_f32_16x16x32_bf16 v[94:97], v[130:133], v[186:189], v[94:97]
	v_mfma_f32_16x16x32_bf16 v[90:93], v[138:141], v[186:189], v[90:93]
	v_mfma_f32_16x16x32_bf16 v[78:81], v[130:133], v[194:197], v[78:81]
	v_mfma_f32_16x16x32_bf16 v[74:77], v[138:141], v[194:197], v[74:77]
	v_mfma_f32_16x16x32_bf16 v[126:129], v[134:137], v[166:169], v[126:129]
	v_mfma_f32_16x16x32_bf16 v[122:125], v[142:145], v[166:169], v[122:125]
	v_mfma_f32_16x16x32_bf16 v[110:113], v[134:137], v[182:185], v[110:113]
	v_mfma_f32_16x16x32_bf16 v[106:109], v[142:145], v[182:185], v[106:109]
	v_mfma_f32_16x16x32_bf16 v[94:97], v[134:137], v[190:193], v[94:97]
	v_mfma_f32_16x16x32_bf16 v[90:93], v[142:145], v[190:193], v[90:93]
	v_mfma_f32_16x16x32_bf16 v[78:81], v[134:137], v[198:201], v[78:81]
	v_mfma_f32_16x16x32_bf16 v[74:77], v[142:145], v[198:201], v[74:77]
	s_setprio 0
	s_setprio 1
	v_mfma_f32_16x16x32_bf16 v[118:121], v[146:149], v[162:165], v[118:121]
	v_mfma_f32_16x16x32_bf16 v[114:117], v[154:157], v[162:165], v[114:117]
	v_mfma_f32_16x16x32_bf16 v[102:105], v[146:149], v[178:181], v[102:105]
	v_mfma_f32_16x16x32_bf16 v[98:101], v[154:157], v[178:181], v[98:101]
	v_mfma_f32_16x16x32_bf16 v[86:89], v[146:149], v[186:189], v[86:89]
	v_mfma_f32_16x16x32_bf16 v[82:85], v[154:157], v[186:189], v[82:85]
	v_mfma_f32_16x16x32_bf16 v[70:73], v[146:149], v[194:197], v[70:73]
	v_mfma_f32_16x16x32_bf16 v[66:69], v[154:157], v[194:197], v[66:69]
	v_mfma_f32_16x16x32_bf16 v[118:121], v[150:153], v[166:169], v[118:121]
	v_mfma_f32_16x16x32_bf16 v[114:117], v[158:161], v[166:169], v[114:117]
	v_mfma_f32_16x16x32_bf16 v[102:105], v[150:153], v[182:185], v[102:105]
	v_mfma_f32_16x16x32_bf16 v[98:101], v[158:161], v[182:185], v[98:101]
	v_mfma_f32_16x16x32_bf16 v[86:89], v[150:153], v[190:193], v[86:89]
	v_mfma_f32_16x16x32_bf16 v[82:85], v[158:161], v[190:193], v[82:85]
	v_mfma_f32_16x16x32_bf16 v[70:73], v[150:153], v[198:201], v[70:73]
	v_mfma_f32_16x16x32_bf16 v[66:69], v[158:161], v[198:201], v[66:69]
	s_setprio 0
	s_barrier
; #define PG8_STAGE(bufoff, gbase, voff) do { const char* _gb = (const char*)(gbase); asm volatile("" : "+s"(_gb)); _Pragma("unroll") for (int _i = 0; _i < 2; ++_i) { \
;         unsigned _vo = (voff)[_i]; asm volatile("" : "+v"(_vo));     \
;         __builtin_amdgcn_global_load_lds((const unsigned*)(_gb + _vo), (LAS unsigned*)(lds + (bufoff) + ldsw + _i * 8192), 16, 0, 0); } } while (0)
; #define PG8_LDA(dst, b, h) do { _Pragma("unroll") for (int m = 0; m < 4; ++m) _Pragma("unroll") for (int k = 0; k < 2; ++k) dst[m][k] = *(const LAS bf16x8*)(lds + PG8_SA(b, h) + aoff + m * 2048 + k * 1024); } while (0)
; #define PG8_MMA(ai, bj, At, Bt) do { __builtin_amdgcn_s_setprio(1); _Pragma("unroll") for (int m = 0; m < 4; ++m) _Pragma("unroll") for (int n = 0; n < 2; ++n) _Pragma("unroll") for (int k = 0; k < 2; ++k) \
;         acc[ai][bj][m][n] = __builtin_amdgcn_mfma_f32_16x16x32_bf16(Bt[n][k], At[m][k], acc[ai][bj][m][n], 0, 0, 0); __builtin_amdgcn_s_setprio(0); } while (0)
; #define PG8_WAIT_V(n) asm volatile("s_waitcnt vmcnt(" #n ")" ::: "memory")
; #define PG8_WAIT_L(n) asm volatile("s_waitcnt lgkmcnt(" #n ")" ::: "memory")
; #define PG8_BAR __builtin_amdgcn_s_barrier()
; #define PG8_SCHED __builtin_amdgcn_sched_barrier(0)
; template <class Epi, class Sched>
; DI void gemm_phase(int wv, LAS unsigned char* lds, const Gemm g, const Sched& S, const Epi& E) {
;     ...
;             PG8_LDA(At, 1, 1); PG8_STAGE(PG8_SB(1, 0), b3, voffB); PG8_STAGE(PG8_SB(1, 1), b3 + hstepB, voffB); PG8_STAGE(PG8_SA(1, 0), a3, voffA);
;             PG8_WAIT_V(8); PG8_WAIT_L(0); PG8_BAR; PG8_MMA(1, 0, At, B0); PG8_MMA(1, 1, At, B1); PG8_BAR; PG8_SCHED;
	s_add_u32 s36, s34, 0x80
	s_addc_u32 s37, s35, 0
	v_mov_b32_e32 v0, v173
	s_add_i32 s45, s45, s54
	ds_read_b128 v[162:165], v177 offset:49152
	ds_read_b128 v[166:169], v177 offset:50176
	ds_read_b128 v[178:181], v177 offset:51200
	ds_read_b128 v[182:185], v177 offset:52224
	ds_read_b128 v[186:189], v177 offset:53248
	ds_read_b128 v[190:193], v177 offset:54272
	ds_read_b128 v[194:197], v177 offset:55296
	ds_read_b128 v[198:201], v177 offset:56320
	s_mov_b32 m0, s45
	s_nop 0
	global_load_lds_dwordx4 v0, s[36:37]
	v_mov_b32_e32 v0, v175
	s_add_i32 m0, s45, 0x2000
	s_add_u32 s34, s34, 0x40080
	global_load_lds_dwordx4 v0, s[36:37]
	s_addc_u32 s35, s35, 0
	v_mov_b32_e32 v0, v173
	s_add_i32 s36, s48, s54
	s_mov_b32 m0, s36
	s_nop 0
	global_load_lds_dwordx4 v0, s[34:35]
	v_mov_b32_e32 v0, v175
	s_add_i32 m0, s36, 0x2000
	s_nop 0
	global_load_lds_dwordx4 v0, s[34:35]
	v_mov_b32_e32 v0, v172
	s_mov_b32 m0, s67
	s_nop 0
	global_load_lds_dwordx4 v0, s[6:7]
	v_mov_b32_e32 v0, v174
	s_mov_b32 m0, s69
	s_nop 0
	global_load_lds_dwordx4 v0, s[6:7]
	s_waitcnt vmcnt(8)
	s_waitcnt lgkmcnt(0)
	s_barrier
	s_setprio 1
	s_waitcnt lgkmcnt(0)
	v_mfma_f32_16x16x32_bf16 v[62:65], v[130:133], v[162:165], v[62:65]
	v_mfma_f32_16x16x32_bf16 v[58:61], v[138:141], v[162:165], v[58:61]
	v_mfma_f32_16x16x32_bf16 v[46:49], v[130:133], v[178:181], v[46:49]
	v_mfma_f32_16x16x32_bf16 v[42:45], v[138:141], v[178:181], v[42:45]
	v_mfma_f32_16x16x32_bf16 v[30:33], v[130:133], v[186:189], v[30:33]
	v_mfma_f32_16x16x32_bf16 v[26:29], v[138:141], v[186:189], v[26:29]
	v_mfma_f32_16x16x32_bf16 v[14:17], v[130:133], v[194:197], v[14:17]
	v_mfma_f32_16x16x32_bf16 v[10:13], v[138:141], v[194:197], v[10:13]
	v_mfma_f32_16x16x32_bf16 v[62:65], v[134:137], v[166:169], v[62:65]
	v_mfma_f32_16x16x32_bf16 v[58:61], v[142:145], v[166:169], v[58:61]
	v_mfma_f32_16x16x32_bf16 v[46:49], v[134:137], v[182:185], v[46:49]
	v_mfma_f32_16x16x32_bf16 v[42:45], v[142:145], v[182:185], v[42:45]
	v_mfma_f32_16x16x32_bf16 v[30:33], v[134:137], v[190:193], v[30:33]
	v_mfma_f32_16x16x32_bf16 v[26:29], v[142:145], v[190:193], v[26:29]
	v_mfma_f32_16x16x32_bf16 v[14:17], v[134:137], v[198:201], v[14:17]
	v_mfma_f32_16x16x32_bf16 v[10:13], v[142:145], v[198:201], v[10:13]
	s_setprio 0
	s_setprio 1
	v_mfma_f32_16x16x32_bf16 v[54:57], v[146:149], v[162:165], v[54:57]
	v_mfma_f32_16x16x32_bf16 v[50:53], v[154:157], v[162:165], v[50:53]
	v_mfma_f32_16x16x32_bf16 v[38:41], v[146:149], v[178:181], v[38:41]
	v_mfma_f32_16x16x32_bf16 v[34:37], v[154:157], v[178:181], v[34:37]
	v_mfma_f32_16x16x32_bf16 v[22:25], v[146:149], v[186:189], v[22:25]
	v_mfma_f32_16x16x32_bf16 v[18:21], v[154:157], v[186:189], v[18:21]
	v_mfma_f32_16x16x32_bf16 v[6:9], v[146:149], v[194:197], v[6:9]
	v_mfma_f32_16x16x32_bf16 v[2:5], v[154:157], v[194:197], v[2:5]
	v_mfma_f32_16x16x32_bf16 v[54:57], v[150:153], v[166:169], v[54:57]
	v_mfma_f32_16x16x32_bf16 v[50:53], v[158:161], v[166:169], v[50:53]
	v_mfma_f32_16x16x32_bf16 v[38:41], v[150:153], v[182:185], v[38:41]
	v_mfma_f32_16x16x32_bf16 v[34:37], v[158:161], v[182:185], v[34:37]
	v_mfma_f32_16x16x32_bf16 v[22:25], v[150:153], v[190:193], v[22:25]
	v_mfma_f32_16x16x32_bf16 v[18:21], v[158:161], v[190:193], v[18:21]
	v_mfma_f32_16x16x32_bf16 v[6:9], v[150:153], v[198:201], v[6:9]
	v_mfma_f32_16x16x32_bf16 v[2:5], v[158:161], v[198:201], v[2:5]
	s_setprio 0
	s_barrier
	s_add_i32 s44, s44, 2
	s_add_u32 s38, s38, 0x100
	s_addc_u32 s39, s39, 0
	s_add_u32 s4, s4, 0x100
	s_addc_u32 s5, s5, 0
	s_cmp_gt_u32 s44, 13

; #define EPI_SCHED() __builtin_amdgcn_sched_barrier(0)
; template <int STRIDE, int P0, int NP4>
; DI void rstd8(const float* parts, size_t row0, float invK, int fq, float (&rs)[2][4]) {
;     f32x4 v[2][4];
; #pragma unroll
;     for (int ai = 0; ai < 2; ++ai)
; #pragma unroll
;         for (int m = 0; m < 4; ++m) {
;             const float* p = parts + (row0 + ai * 128 + m * 16) * STRIDE + P0;
;             if (NP4 == 1) v[ai][m] = *(const f32x4*)p;
;             else if (fq < NP4) v[ai][m] = *(const f32x4*)(p + 4 * fq);
;             else v[ai][m] = (f32x4){0.f, 0.f, 0.f, 0.f};
;         }
; #pragma unroll
;     for (int ai = 0; ai < 2; ++ai)
; #pragma unroll
;         for (int m = 0; m < 4; ++m) {
;             float t = (v[ai][m].x + v[ai][m].y) + (v[ai][m].z + v[ai][m].w);
;             if (NP4 > 1) { t += __shfl_xor(t, 16); t += __shfl_xor(t, 32); }
;             rs[ai][m] = rsqrtf(t * invK + EPS);
;         }
;     DI void operator()(const AccT& acc, const Unit& u, int wr, int wc, int fr, int fq) const {
;     ...
;         float rs[2][4]; rstd8<12, 4, 2>(ssq, row0, 1.f / 384.f, fq, rs);
; #pragma unroll
;         for (int bj = 0; bj < 2; ++bj) {
;             const int col = u.pn * 256 + bj * 128 + wc * 32 + fq * 8;
;             const int d0 = col % 96; const bool do_rope = d0 >= 64; const int i0 = do_rope ? (d0 - 64) >> 1 : 0;
; #pragma unroll
;             for (int ai = 0; ai < 2; ++ai) {
;                 EPI_SCHED();
;                 f32x4 cs[4], sn[4];
;                 if (do_rope) {
; #pragma unroll
;                     for (int m = 0; m < 4; ++m) { const int s = (int)((row0 + ai * 128 + m * 16) & 2047); cs[m] = *(const f32x4*)(rope + s * 16 + i0); sn[m] = *(const f32x4*)(rope + 32768 + s * 16 + i0); }
.LBB0_2652:
	s_mov_b32 s3, -1
	v_mov_b32_e32 v86, 0
	v_mbcnt_lo_u32_b32 v0, s3, 0
	v_mbcnt_hi_u32_b32 v82, s3, v0
	s_ashr_i32 s3, s2, 31
	s_lshl_b64 s[2:3], s[2:3], 8
	s_add_u32 s2, s2, s45
	v_ashrrev_i32_e32 v0, 4, v82
	s_addc_u32 s3, s3, s49
	v_lshlrev_b32_e32 v112, 2, v0
	v_and_or_b32 v195, v82, 15, s2
	v_mov_b32_e32 v194, s3
	v_cmp_gt_i32_e64 s[2:3], 2, v0
	v_ashrrev_i32_e32 v113, 31, v112
	v_mov_b32_e32 v82, 0
	v_mov_b32_e32 v126, 0
	v_mov_b32_e32 v127, 0
	v_mov_b32_e32 v87, 0
	v_mov_b32_e32 v82, 0
	v_mov_b32_e32 v83, 0
	v_mov_b32_e32 v84, 0
	v_mov_b32_e32 v85, 0
	v_mov_b32_e32 v86, 0
	v_mov_b32_e32 v87, 0
	v_mov_b32_e32 v88, 0
	v_mov_b32_e32 v89, 0
	v_mov_b32_e32 v98, 0
	v_mov_b32_e32 v99, 0
	v_mov_b32_e32 v100, 0
	v_mov_b32_e32 v101, 0
	v_mov_b32_e32 v102, 0
	v_mov_b32_e32 v103, 0
	v_mov_b32_e32 v104, 0
	v_mov_b32_e32 v105, 0
	v_mov_b32_e32 v106, 0
	v_mov_b32_e32 v107, 0
	v_mov_b32_e32 v108, 0
	v_mov_b32_e32 v109, 0
	v_mov_b32_e32 v110, 0
	v_mov_b32_e32 v111, 0
	v_mov_b32_e32 v122, 0
	v_mov_b32_e32 v123, 0
	v_mov_b32_e32 v124, 0
	v_mov_b32_e32 v125, 0
	v_mov_b32_e32 v126, 0
	v_mov_b32_e32 v127, 0
	v_mov_b32_e32 v128, 0
	v_mov_b32_e32 v129, 0
	v_mov_b32_e32 v162, 0
	v_mov_b32_e32 v163, 0
	v_mad_u64_u32 v[164:165], s[24:25], v195, 48, s[12:13]
	v_mov_b32_e32 v166, v165
	v_mad_u64_u32 v[166:167], s[24:25], v194, 48, v[166:167]
	v_mov_b32_e32 v165, v166
	v_lshl_add_u64 v[164:165], v[112:113], 2, v[164:165]
	v_add_co_u32_e32 v166, vcc, 0x1000, v164
	s_nop 1
	v_addc_co_u32_e32 v167, vcc, 0, v165, vcc
	v_add_co_u32_e32 v184, vcc, 0x2000, v164
	s_nop 1
	v_addc_co_u32_e32 v185, vcc, 0, v165, vcc
	s_and_saveexec_b64 s[4:5], s[2:3]
	global_load_dwordx4 v[86:89], v[164:165], off offset:16
	global_load_dwordx4 v[82:85], v[164:165], off offset:784
	global_load_dwordx4 v[102:105], v[164:165], off offset:1552
	global_load_dwordx4 v[98:101], v[164:165], off offset:2320
	global_load_dwordx4 v[108:111], v[166:167], off offset:2064
	global_load_dwordx4 v[168:171], v[166:167], off offset:2832
	global_load_dwordx4 v[122:125], v[166:167], off offset:3600
	global_load_dwordx4 v[172:175], v[184:185], off offset:272
	s_waitcnt vmcnt(0)
	v_mov_b32_e32 v126, v87
	v_mov_b32_e32 v127, v88
	v_mov_b32_e32 v87, v89
	v_mov_b32_e32 v88, v83
	v_mov_b32_e32 v89, v84
	v_mov_b32_e32 v83, v85
	v_mov_b32_e32 v84, v103
	v_mov_b32_e32 v85, v104
	v_mov_b32_e32 v103, v105
	v_mov_b32_e32 v128, v99
	v_mov_b32_e32 v129, v100
	v_mov_b32_e32 v99, v101
	v_mov_b32_e32 v100, v109
	v_mov_b32_e32 v101, v110
	v_mov_b32_e32 v109, v111
	v_mov_b32_e32 v104, v168
	v_mov_b32_e32 v162, v169
	v_mov_b32_e32 v163, v170
	v_mov_b32_e32 v105, v171
	v_mov_b32_e32 v106, v123
	v_mov_b32_e32 v107, v124
	v_mov_b32_e32 v123, v125
	v_mov_b32_e32 v110, v172
	v_mov_b32_e32 v124, v173
	v_mov_b32_e32 v125, v174
	v_mov_b32_e32 v111, v175
.LBB0_2668:
	s_or_b64 exec, exec, s[4:5]
	v_pk_add_f32 v[86:87], v[126:127], v[86:87]
	v_pk_add_f32 v[82:83], v[88:89], v[82:83]
	v_xor_b32_e32 v112, 16, v207
	v_mov_b32_e32 v88, v82
	v_mov_b32_e32 v89, v86
	v_mov_b32_e32 v86, v83
	v_cmp_lt_i32_e32 vcc, v112, v222
	v_pk_add_f32 v[82:83], v[88:89], v[86:87]
	v_pk_add_f32 v[84:85], v[84:85], v[102:103]
	v_pk_add_f32 v[88:89], v[128:129], v[98:99]
	v_cndmask_b32_e32 v112, v207, v112, vcc
	v_mov_b32_e32 v98, v88
	v_mov_b32_e32 v99, v84
	v_mov_b32_e32 v84, v89
	v_lshlrev_b32_e32 v112, 2, v112
	v_pk_add_f32 v[84:85], v[98:99], v[84:85]
	ds_bpermute_b32 v87, v112, v83
	ds_bpermute_b32 v86, v112, v82
	ds_bpermute_b32 v89, v112, v85
	ds_bpermute_b32 v88, v112, v84
	s_lshl_b32 s2, s55, 8
	s_or_b32 s2, s2, s46
	s_waitcnt lgkmcnt(0)
	v_pk_add_f32 v[166:167], v[82:83], v[86:87]
	v_pk_add_f32 v[82:83], v[100:101], v[108:109]
	v_pk_add_f32 v[180:181], v[84:85], v[88:89]
	v_pk_add_f32 v[84:85], v[162:163], v[104:105]
	v_mov_b32_e32 v87, v82
	v_mov_b32_e32 v86, v84
	v_mov_b32_e32 v82, v85
	v_pk_add_f32 v[82:83], v[86:87], v[82:83]
	v_pk_add_f32 v[86:87], v[106:107], v[122:123]
	v_pk_add_f32 v[88:89], v[124:125], v[110:111]
	v_mov_b32_e32 v99, v86
	v_mov_b32_e32 v98, v88
	v_mov_b32_e32 v86, v89
	v_pk_add_f32 v[86:87], v[98:99], v[86:87]
	ds_bpermute_b32 v85, v112, v83
	ds_bpermute_b32 v84, v112, v82
	ds_bpermute_b32 v89, v112, v87
	ds_bpermute_b32 v88, v112, v86
	v_cmp_lt_i32_e32 vcc, v223, v222
	v_lshl_add_u32 v164, v0, 3, s2
	s_mov_b32 s2, 0x2aaaaaab
	v_cndmask_b32_e32 v113, v207, v223, vcc
	v_mul_hi_i32 v0, v164, s2
	v_lshlrev_b32_e32 v102, 2, v113
	s_waitcnt lgkmcnt(0)
	v_pk_add_f32 v[172:173], v[82:83], v[84:85]
	v_pk_add_f32 v[168:169], v[86:87], v[88:89]
	v_lshrrev_b32_e32 v82, 31, v0
	v_lshrrev_b32_e32 v0, 4, v0
	ds_bpermute_b32 v185, v102, v167
	ds_bpermute_b32 v184, v102, v166
	ds_bpermute_b32 v183, v102, v181
	ds_bpermute_b32 v182, v102, v180
	ds_bpermute_b32 v175, v102, v173
	ds_bpermute_b32 v174, v102, v172
	ds_bpermute_b32 v171, v102, v169
	ds_bpermute_b32 v170, v102, v168
	v_add_u32_e32 v0, v0, v82
	s_movk_i32 s2, 0x60
	v_mul_lo_u32 v0, v0, s2
	v_sub_u32_e32 v0, v164, v0
	v_subrev_u32_e32 v82, 64, v0
	v_lshlrev_b32_e32 v196, 4, v195
	v_lshrrev_b32_e32 v82, 1, v82
	v_cmp_lt_i32_e32 vcc, 63, v0
	s_nop 1
	v_cndmask_b32_e32 v0, 0, v82, vcc
	v_mov_b32_e32 v122, 0
	v_and_b32_e32 v84, 0x7cf0, v196
	v_lshlrev_b64 v[82:83], 2, v[0:1]
	v_lshl_add_u64 v[178:179], s[6:7], 0, v[82:83]
	v_lshl_add_u64 v[176:177], s[18:19], 0, v[82:83]
	v_lshlrev_b32_e32 v162, 2, v84
	v_mov_b32_e32 v123, 0
	v_mov_b32_e32 v124, v122
	v_mov_b32_e32 v125, v122
	v_mov_b32_e32 v106, v122
	v_mov_b32_e32 v107, v122
	v_mov_b32_e32 v108, v122
	v_mov_b32_e32 v109, v122
	v_mov_b32_e32 v98, v122
	v_mov_b32_e32 v99, v122
	v_mov_b32_e32 v100, v122
	v_mov_b32_e32 v101, v122
	v_mov_b32_e32 v82, v122
	v_mov_b32_e32 v83, v122
	v_mov_b32_e32 v84, v122
	v_mov_b32_e32 v85, v122
	s_and_saveexec_b64 s[2:3], vcc
	s_cbranch_execz .LBB0_2670
	v_mov_b32_e32 v163, v1
	v_lshl_add_u64 v[82:83], v[178:179], 0, v[162:163]
	v_lshl_add_u64 v[86:87], v[176:177], 0, v[162:163]
	global_load_dwordx4 v[122:125], v[82:83], off
	global_load_dwordx4 v[106:109], v[82:83], off offset:1024
	global_load_dwordx4 v[126:129], v[86:87], off
	global_load_dwordx4 v[110:113], v[86:87], off offset:1024
	global_load_dwordx4 v[98:101], v[82:83], off offset:2048
	s_nop 0
	global_load_dwordx4 v[82:85], v[82:83], off offset:3072
	s_nop 0
	global_load_dwordx4 v[102:105], v[86:87], off offset:2048
	s_nop 0
	global_load_dwordx4 v[86:89], v[86:87], off offset:3072

; DI u32x4 pk8(f32x4 a, f32x4 b) { u32x4 o; o.x = pk2(a.x, a.y); o.y = pk2(a.z, a.w); o.z = pk2(b.x, b.y); o.w = pk2(b.z, b.w); return o; }
; template <int STRIDE, int P0, int NP4>
; DI void rstd8(const float* parts, size_t row0, float invK, int fq, float (&rs)[2][4]) {
;     ...
;             float t = (v[ai][m].x + v[ai][m].y) + (v[ai][m].z + v[ai][m].w);
;             if (NP4 > 1) { t += __shfl_xor(t, 16); t += __shfl_xor(t, 32); }
;             rs[ai][m] = rsqrtf(t * invK + EPS);
;     DI void operator()(const AccT& acc, const Unit& u, int wr, int wc, int fr, int fq) const {
;     ...
; #pragma unroll
;                 for (int m = 0; m < 4; ++m) {
;                     const size_t row = row0 + ai * 128 + m * 16;
;                     f32x4 a = acc[ai][bj][m][0] * rs[ai][m], b = acc[ai][bj][m][1] * rs[ai][m];
;                     if (do_rope) rope4(a, b, cs[m], sn[m]);
;                     *(u32x4*)(q + row * 1536 + col) = pk8(a, b);
.LBB0_2672:
	s_or_b64 exec, exec, s[4:5]
	v_mul_f32_e32 v0, 0x4b800000, v184
	v_cndmask_b32_e64 v0, v184, v0, s[2:3]
	v_rsq_f32_e32 v0, v0
	v_cvt_pk_bf16_f32 v185, v186, v187
	v_cvt_pk_bf16_f32 v186, v156, v157
	v_mov_b64_e32 v[156:157], s[14:15]
	v_mul_f32_e32 v154, 0x45800000, v0
	v_cvt_pk_bf16_f32 v184, v158, v159
	v_cndmask_b32_e64 v154, v0, v154, s[2:3]
	v_mad_u64_u32 v[158:159], s[2:3], v195, s77, v[156:157]
	v_mov_b32_e32 v0, v159
	v_mad_u64_u32 v[156:157], s[2:3], v194, s77, v[0:1]
	v_ashrrev_i32_e32 v165, 31, v164
	v_mov_b32_e32 v159, v156
	v_cvt_pk_bf16_f32 v187, v160, v161
	v_lshl_add_u64 v[156:157], v[164:165], 1, v[158:159]
	flat_store_dwordx4 v[156:157], v[184:187]
	v_pk_mul_f32 v[160:161], v[148:149], v[154:155] op_sel_hi:[1,0]
	v_pk_mul_f32 v[148:149], v[146:147], v[154:155] op_sel_hi:[1,0]
	v_pk_mul_f32 v[184:185], v[152:153], v[154:155] op_sel_hi:[1,0]
	v_pk_mul_f32 v[152:153], v[150:151], v[154:155] op_sel_hi:[1,0]
	s_and_saveexec_b64 s[2:3], vcc
	s_cbranch_execz .LBB0_2674
	s_waitcnt vmcnt(3)
	v_mov_b32_e32 v186, v107
	v_mov_b32_e32 v187, v111
	v_mul_f32_e32 v0, v185, v111
	v_pk_fma_f32 v[186:187], v[184:185], v[186:187], v[0:1] op_sel_hi:[1,1,0] neg_lo:[0,0,1] neg_hi:[0,0,1]
	v_mov_b32_e32 v194, v111
	v_mov_b32_e32 v195, v107
	v_mul_f32_e32 v0, v185, v107
	v_pk_fma_f32 v[194:195], v[184:185], v[194:195], v[0:1] op_sel_hi:[1,1,0]
	v_mov_b32_e32 v200, v109
	v_mov_b32_e32 v201, v113
	v_mul_f32_e32 v0, v161, v113
	v_pk_mul_f32 v[146:147], v[152:153], v[110:111] op_sel:[1,0] op_sel_hi:[0,0]
	v_pk_mul_f32 v[184:185], v[148:149], v[112:113] op_sel:[1,0] op_sel_hi:[0,0]
	v_pk_fma_f32 v[200:201], v[160:161], v[200:201], v[0:1] op_sel_hi:[1,1,0] neg_lo:[0,0,1] neg_hi:[0,0,1]
	v_mov_b32_e32 v202, v113
	v_mov_b32_e32 v203, v109
	v_mul_f32_e32 v0, v161, v109
	v_pk_mul_f32 v[150:151], v[152:153], v[106:107]
	v_pk_fma_f32 v[152:153], v[152:153], v[106:107], v[146:147] op_sel_hi:[1,0,1]
	v_pk_mul_f32 v[198:199], v[148:149], v[108:109]
	v_pk_fma_f32 v[148:149], v[148:149], v[108:109], v[184:185] op_sel_hi:[1,0,1]
	v_pk_fma_f32 v[202:203], v[160:161], v[202:203], v[0:1] op_sel_hi:[1,1,0]
	v_sub_f32_e32 v148, v198, v184
	v_sub_f32_e32 v152, v150, v146
	v_mov_b32_e32 v160, v200
	v_mov_b32_e32 v161, v202
	v_mov_b32_e32 v184, v186
	v_mov_b32_e32 v185, v194
.LBB0_2674:
	s_or_b64 exec, exec, s[2:3]
	v_pk_add_f32 v[146:147], v[180:181], v[182:183]
	s_mov_b32 s2, 0x3b2aaaab
	v_mov_b32_e32 v0, 0x358637bd
	v_pk_fma_f32 v[150:151], v[146:147], s[2:3], v[0:1] op_sel_hi:[1,0,0]
	v_cvt_pk_bf16_f32 v182, v148, v149
	v_mul_f32_e32 v0, 0x4b800000, v151
	v_cmp_gt_f32_e64 s[4:5], s42, v151
	v_cvt_pk_bf16_f32 v180, v152, v153
	v_cmp_gt_f32_e64 s[2:3], s42, v150
	v_cndmask_b32_e64 v0, v151, v0, s[4:5]
	v_rsq_f32_e32 v0, v0
	v_cvt_pk_bf16_f32 v181, v184, v185
	v_cvt_pk_bf16_f32 v183, v160, v161
	v_mul_f32_e32 v146, 0x45800000, v0
	v_cndmask_b32_e64 v146, v0, v146, s[4:5]
	s_mov_b64 s[4:5], 0xc000
	v_lshl_add_u64 v[148:149], v[158:159], 0, s[4:5]
	v_lshl_add_u64 v[152:153], v[164:165], 1, v[148:149]
	v_pk_mul_f32 v[144:145], v[144:145], v[146:147] op_sel_hi:[1,0]
	v_pk_mul_f32 v[142:143], v[142:143], v[146:147] op_sel_hi:[1,0]
	v_pk_mul_f32 v[140:141], v[140:141], v[146:147] op_sel_hi:[1,0]
	v_pk_mul_f32 v[138:139], v[138:139], v[146:147] op_sel_hi:[1,0]
	flat_store_dwordx4 v[152:153], v[180:183]
	s_and_saveexec_b64 s[4:5], vcc
	s_cbranch_execz .LBB0_2676
	s_waitcnt vmcnt(3)
	v_mov_b32_e32 v180, v99
	v_mov_b32_e32 v181, v103
	v_mul_f32_e32 v0, v145, v103
	v_pk_fma_f32 v[180:181], v[144:145], v[180:181], v[0:1] op_sel_hi:[1,1,0] neg_lo:[0,0,1] neg_hi:[0,0,1]
	v_mov_b32_e32 v182, v103
	v_mov_b32_e32 v183, v99
	v_mul_f32_e32 v0, v145, v99
	v_pk_fma_f32 v[182:183], v[144:145], v[182:183], v[0:1] op_sel_hi:[1,1,0]
	v_mov_b32_e32 v186, v101
	v_mov_b32_e32 v187, v105
	v_mul_f32_e32 v0, v141, v105
	v_pk_mul_f32 v[152:153], v[142:143], v[102:103] op_sel:[1,0] op_sel_hi:[0,0]
	v_pk_mul_f32 v[144:145], v[138:139], v[104:105] op_sel:[1,0] op_sel_hi:[0,0]
	v_pk_fma_f32 v[186:187], v[140:141], v[186:187], v[0:1] op_sel_hi:[1,1,0] neg_lo:[0,0,1] neg_hi:[0,0,1]
	v_mov_b32_e32 v194, v105
	v_mov_b32_e32 v195, v101
	v_mul_f32_e32 v0, v141, v101
	v_pk_mul_f32 v[160:161], v[142:143], v[98:99]
	v_pk_fma_f32 v[142:143], v[142:143], v[98:99], v[152:153] op_sel_hi:[1,0,1]
	v_pk_mul_f32 v[184:185], v[138:139], v[100:101]
	v_pk_fma_f32 v[138:139], v[138:139], v[100:101], v[144:145] op_sel_hi:[1,0,1]
	v_pk_fma_f32 v[194:195], v[140:141], v[194:195], v[0:1] op_sel_hi:[1,1,0]
	v_sub_f32_e32 v138, v184, v144
	v_sub_f32_e32 v142, v160, v152
	v_mov_b32_e32 v140, v186
	v_mov_b32_e32 v141, v194
	v_mov_b32_e32 v144, v180
	v_mov_b32_e32 v145, v182
; DI u32x4 pk8(f32x4 a, f32x4 b) { u32x4 o; o.x = pk2(a.x, a.y); o.y = pk2(a.z, a.w); o.z = pk2(b.x, b.y); o.w = pk2(b.z, b.w); return o; }
;     DI void operator()(const AccT& acc, const Unit& u, int wr, int wc, int fr, int fq) const {
;     ...
;                 if (do_rope) {
; #pragma unroll
;                     for (int m = 0; m < 4; ++m) { const int s = (int)((row0 + ai * 128 + m * 16) & 2047); cs[m] = *(const f32x4*)(rope + s * 16 + i0); sn[m] = *(const f32x4*)(rope + 32768 + s * 16 + i0); }
;                 }
; #pragma unroll
;                 for (int m = 0; m < 4; ++m) {
;                     const size_t row = row0 + ai * 128 + m * 16;
;                     f32x4 a = acc[ai][bj][m][0] * rs[ai][m], b = acc[ai][bj][m][1] * rs[ai][m];
;                     if (do_rope) rope4(a, b, cs[m], sn[m]);
;                     *(u32x4*)(q + row * 1536 + col) = pk8(a, b);
.LBB0_2676:
	s_or_b64 exec, exec, s[4:5]
	v_mul_f32_e32 v0, 0x4b800000, v150
	v_cndmask_b32_e64 v0, v150, v0, s[2:3]
	v_rsq_f32_e32 v0, v0
	v_cvt_pk_bf16_f32 v142, v142, v143
	v_cvt_pk_bf16_f32 v143, v144, v145
	v_cvt_pk_bf16_f32 v144, v138, v139
	v_mul_f32_e32 v138, 0x45800000, v0
	v_cndmask_b32_e64 v138, v0, v138, s[2:3]
	s_mov_b64 s[2:3], 0x18000
	v_cvt_pk_bf16_f32 v145, v140, v141
	v_lshl_add_u64 v[140:141], v[158:159], 0, s[2:3]
	v_lshl_add_u64 v[150:151], v[164:165], 1, v[140:141]
	v_pk_mul_f32 v[136:137], v[136:137], v[138:139] op_sel_hi:[1,0]
	v_pk_mul_f32 v[134:135], v[134:135], v[138:139] op_sel_hi:[1,0]
	v_pk_mul_f32 v[132:133], v[132:133], v[138:139] op_sel_hi:[1,0]
	v_pk_mul_f32 v[130:131], v[130:131], v[138:139] op_sel_hi:[1,0]
	flat_store_dwordx4 v[150:151], v[142:145]
	s_and_saveexec_b64 s[2:3], vcc
	s_cbranch_execz .LBB0_2678
	s_waitcnt vmcnt(3)
	v_mov_b32_e32 v150, v83
	v_mov_b32_e32 v151, v87
	v_mul_f32_e32 v0, v137, v87
	v_pk_fma_f32 v[150:151], v[136:137], v[150:151], v[0:1] op_sel_hi:[1,1,0] neg_lo:[0,0,1] neg_hi:[0,0,1]
	v_mov_b32_e32 v152, v87
	v_mov_b32_e32 v153, v83
	v_mul_f32_e32 v0, v137, v83
	v_pk_fma_f32 v[152:153], v[136:137], v[152:153], v[0:1] op_sel_hi:[1,1,0]
	v_mov_b32_e32 v180, v85
	v_mov_b32_e32 v181, v89
	v_mul_f32_e32 v0, v133, v89
	v_pk_mul_f32 v[142:143], v[134:135], v[86:87] op_sel:[1,0] op_sel_hi:[0,0]
	v_pk_mul_f32 v[136:137], v[130:131], v[88:89] op_sel:[1,0] op_sel_hi:[0,0]
	v_pk_fma_f32 v[180:181], v[132:133], v[180:181], v[0:1] op_sel_hi:[1,1,0] neg_lo:[0,0,1] neg_hi:[0,0,1]
	v_mov_b32_e32 v182, v89
	v_mov_b32_e32 v183, v85
	v_mul_f32_e32 v0, v133, v85
	v_pk_mul_f32 v[144:145], v[134:135], v[82:83]
	v_pk_fma_f32 v[134:135], v[134:135], v[82:83], v[142:143] op_sel_hi:[1,0,1]
	v_pk_mul_f32 v[160:161], v[130:131], v[84:85]
	v_pk_fma_f32 v[130:131], v[130:131], v[84:85], v[136:137] op_sel_hi:[1,0,1]
	v_pk_fma_f32 v[182:183], v[132:133], v[182:183], v[0:1] op_sel_hi:[1,1,0]
	v_sub_f32_e32 v130, v160, v136
	v_sub_f32_e32 v134, v144, v142
	v_mov_b32_e32 v132, v180
	v_mov_b32_e32 v133, v182
	v_mov_b32_e32 v136, v150
	v_mov_b32_e32 v137, v152
.LBB0_2678:
	s_or_b64 exec, exec, s[2:3]
	s_mov_b64 s[2:3], 0x24000
	v_cvt_pk_bf16_f32 v134, v134, v135
	v_cvt_pk_bf16_f32 v135, v136, v137
	v_cvt_pk_bf16_f32 v136, v130, v131
	v_lshl_add_u64 v[130:131], v[158:159], 0, s[2:3]
	v_cvt_pk_bf16_f32 v137, v132, v133
	v_lshl_add_u64 v[132:133], v[164:165], 1, v[130:131]
	flat_store_dwordx4 v[132:133], v[134:137]
	v_add_u32_e32 v0, 0x800, v196
	v_and_b32_e32 v133, 0x7cf0, v0
	s_and_saveexec_b64 s[2:3], vcc
	s_cbranch_execz .LBB0_2680
	v_lshlrev_b32_e32 v0, 2, v133
	s_waitcnt vmcnt(0)
	v_lshl_add_u64 v[82:83], v[178:179], 0, v[0:1]
	v_lshl_add_u64 v[86:87], v[176:177], 0, v[0:1]
	global_load_dwordx4 v[122:125], v[82:83], off
	global_load_dwordx4 v[106:109], v[82:83], off offset:1024
	global_load_dwordx4 v[126:129], v[86:87], off
	global_load_dwordx4 v[110:113], v[86:87], off offset:1024
	global_load_dwordx4 v[98:101], v[82:83], off offset:2048
	s_nop 0
	global_load_dwordx4 v[82:85], v[82:83], off offset:3072
	s_nop 0
	global_load_dwordx4 v[102:105], v[86:87], off offset:2048
	s_nop 0
	global_load_dwordx4 v[86:89], v[86:87], off offset:3072

; DI u32x4 pk8(f32x4 a, f32x4 b) { u32x4 o; o.x = pk2(a.x, a.y); o.y = pk2(a.z, a.w); o.z = pk2(b.x, b.y); o.w = pk2(b.z, b.w); return o; }
;     DI void operator()(const AccT& acc, const Unit& u, int wr, int wc, int fr, int fq) const {
;     ...
;                 if (do_rope) {
; #pragma unroll
;                     for (int m = 0; m < 4; ++m) { const int s = (int)((row0 + ai * 128 + m * 16) & 2047); cs[m] = *(const f32x4*)(rope + s * 16 + i0); sn[m] = *(const f32x4*)(rope + 32768 + s * 16 + i0); }
;                 }
; #pragma unroll
;                 for (int m = 0; m < 4; ++m) {
;                     const size_t row = row0 + ai * 128 + m * 16;
;                     f32x4 a = acc[ai][bj][m][0] * rs[ai][m], b = acc[ai][bj][m][1] * rs[ai][m];
;                     if (do_rope) rope4(a, b, cs[m], sn[m]);
;                     *(u32x4*)(q + row * 1536 + col) = pk8(a, b);
;                 }
.LBB0_2682:
	s_or_b64 exec, exec, s[4:5]
	v_mul_f32_e32 v0, 0x4b800000, v134
	v_cndmask_b32_e64 v0, v134, v0, s[2:3]
	v_rsq_f32_e32 v0, v0
	v_cvt_pk_bf16_f32 v118, v118, v119
	v_cvt_pk_bf16_f32 v119, v120, v121
	v_cvt_pk_bf16_f32 v120, v114, v115
	v_mul_f32_e32 v114, 0x45800000, v0
	v_cndmask_b32_e64 v114, v0, v114, s[2:3]
	s_mov_b64 s[2:3], 0x60000
	v_cvt_pk_bf16_f32 v121, v116, v117
	v_lshl_add_u64 v[116:117], v[158:159], 0, s[2:3]
	v_lshl_add_u64 v[134:135], v[164:165], 1, v[116:117]
	flat_store_dwordx4 v[134:135], v[118:121]
	s_nop 1
	v_pk_mul_f32 v[120:121], v[96:97], v[114:115] op_sel_hi:[1,0]
	v_pk_mul_f32 v[96:97], v[94:95], v[114:115] op_sel_hi:[1,0]
	v_pk_mul_f32 v[118:119], v[92:93], v[114:115] op_sel_hi:[1,0]
	v_pk_mul_f32 v[92:93], v[90:91], v[114:115] op_sel_hi:[1,0]
	s_and_saveexec_b64 s[2:3], vcc
	s_cbranch_execz .LBB0_2684
	s_waitcnt vmcnt(3) lgkmcnt(0)
	v_mov_b32_e32 v134, v107
	v_mov_b32_e32 v135, v111
	v_mul_f32_e32 v0, v121, v111
	v_pk_fma_f32 v[134:135], v[120:121], v[134:135], v[0:1] op_sel_hi:[1,1,0] neg_lo:[0,0,1] neg_hi:[0,0,1]
	v_mov_b32_e32 v136, v111
	v_mov_b32_e32 v137, v107
	v_mul_f32_e32 v0, v121, v107
	v_pk_fma_f32 v[136:137], v[120:121], v[136:137], v[0:1] op_sel_hi:[1,1,0]
	v_mov_b32_e32 v144, v109
	v_mov_b32_e32 v145, v113
	v_mul_f32_e32 v0, v119, v113
	v_pk_mul_f32 v[90:91], v[96:97], v[110:111] op_sel:[1,0] op_sel_hi:[0,0]
	v_pk_mul_f32 v[120:121], v[92:93], v[112:113] op_sel:[1,0] op_sel_hi:[0,0]
	v_pk_fma_f32 v[144:145], v[118:119], v[144:145], v[0:1] op_sel_hi:[1,1,0] neg_lo:[0,0,1] neg_hi:[0,0,1]
	v_mov_b32_e32 v150, v113
	v_mov_b32_e32 v151, v109
	v_mul_f32_e32 v0, v119, v109
	v_pk_mul_f32 v[94:95], v[96:97], v[106:107]
	v_pk_fma_f32 v[96:97], v[96:97], v[106:107], v[90:91] op_sel_hi:[1,0,1]
	v_pk_mul_f32 v[142:143], v[92:93], v[108:109]
	v_pk_fma_f32 v[92:93], v[92:93], v[108:109], v[120:121] op_sel_hi:[1,0,1]
	v_pk_fma_f32 v[150:151], v[118:119], v[150:151], v[0:1] op_sel_hi:[1,1,0]
	v_sub_f32_e32 v92, v142, v120
	v_sub_f32_e32 v96, v94, v90
	v_mov_b32_e32 v118, v144
	v_mov_b32_e32 v119, v150
	v_mov_b32_e32 v120, v134
	v_mov_b32_e32 v121, v136
.LBB0_2684:
	s_or_b64 exec, exec, s[2:3]
	v_pk_add_f32 v[90:91], v[168:169], v[170:171]
	s_mov_b32 s2, 0x3b2aaaab
	v_mov_b32_e32 v0, 0x358637bd
	v_pk_fma_f32 v[94:95], v[90:91], s[2:3], v[0:1] op_sel_hi:[1,0,0]
	v_cvt_pk_bf16_f32 v136, v92, v93
	v_mul_f32_e32 v0, 0x4b800000, v95
	v_cmp_gt_f32_e64 s[4:5], s42, v95
	v_cvt_pk_bf16_f32 v134, v96, v97
	v_cmp_gt_f32_e64 s[2:3], s42, v94
	v_cndmask_b32_e64 v0, v95, v0, s[4:5]
	v_rsq_f32_e32 v0, v0
	v_cvt_pk_bf16_f32 v135, v120, v121
	v_cvt_pk_bf16_f32 v137, v118, v119
	v_mul_f32_e32 v90, 0x45800000, v0
	v_cndmask_b32_e64 v90, v0, v90, s[4:5]
	s_mov_b64 s[4:5], 0x6c000
	v_lshl_add_u64 v[92:93], v[158:159], 0, s[4:5]
	v_lshl_add_u64 v[96:97], v[164:165], 1, v[92:93]
	v_pk_mul_f32 v[80:81], v[80:81], v[90:91] op_sel_hi:[1,0]
	v_pk_mul_f32 v[78:79], v[78:79], v[90:91] op_sel_hi:[1,0]
	v_pk_mul_f32 v[76:77], v[76:77], v[90:91] op_sel_hi:[1,0]
	v_pk_mul_f32 v[74:75], v[74:75], v[90:91] op_sel_hi:[1,0]
	flat_store_dwordx4 v[96:97], v[134:137]
	s_and_saveexec_b64 s[4:5], vcc
	s_cbranch_execz .LBB0_2686
	s_waitcnt vmcnt(3) lgkmcnt(0)
	v_mov_b32_e32 v120, v99
	v_mov_b32_e32 v121, v103
	v_mul_f32_e32 v0, v81, v103
	v_pk_fma_f32 v[120:121], v[80:81], v[120:121], v[0:1] op_sel_hi:[1,1,0] neg_lo:[0,0,1] neg_hi:[0,0,1]
	v_mov_b32_e32 v134, v103
	v_mov_b32_e32 v135, v99
	v_mul_f32_e32 v0, v81, v99
	v_pk_fma_f32 v[134:135], v[80:81], v[134:135], v[0:1] op_sel_hi:[1,1,0]
	v_mov_b32_e32 v142, v101
	v_mov_b32_e32 v143, v105
	v_mul_f32_e32 v0, v77, v105
	v_pk_mul_f32 v[96:97], v[78:79], v[102:103] op_sel:[1,0] op_sel_hi:[0,0]
	v_pk_mul_f32 v[80:81], v[74:75], v[104:105] op_sel:[1,0] op_sel_hi:[0,0]
	v_pk_fma_f32 v[142:143], v[76:77], v[142:143], v[0:1] op_sel_hi:[1,1,0] neg_lo:[0,0,1] neg_hi:[0,0,1]
	v_mov_b32_e32 v144, v105
	v_mov_b32_e32 v145, v101
	v_mul_f32_e32 v0, v77, v101
	v_pk_mul_f32 v[118:119], v[78:79], v[98:99]
	v_pk_fma_f32 v[78:79], v[78:79], v[98:99], v[96:97] op_sel_hi:[1,0,1]
	v_pk_mul_f32 v[136:137], v[74:75], v[100:101]
	v_pk_fma_f32 v[74:75], v[74:75], v[100:101], v[80:81] op_sel_hi:[1,0,1]
	v_pk_fma_f32 v[144:145], v[76:77], v[144:145], v[0:1] op_sel_hi:[1,1,0]
	v_sub_f32_e32 v74, v136, v80
	v_sub_f32_e32 v78, v118, v96
	v_mov_b32_e32 v76, v142
	v_mov_b32_e32 v77, v144
	v_mov_b32_e32 v80, v120
	v_mov_b32_e32 v81, v134
; DI u32x4 pk8(f32x4 a, f32x4 b) { u32x4 o; o.x = pk2(a.x, a.y); o.y = pk2(a.z, a.w); o.z = pk2(b.x, b.y); o.w = pk2(b.z, b.w); return o; }
; #define EPI_SCHED() __builtin_amdgcn_sched_barrier(0)
;     DI void operator()(const AccT& acc, const Unit& u, int wr, int wc, int fr, int fq) const {
;     ...
;             const int col = u.pn * 256 + bj * 128 + wc * 32 + fq * 8;
;             const int d0 = col % 96; const bool do_rope = d0 >= 64; const int i0 = do_rope ? (d0 - 64) >> 1 : 0;
; #pragma unroll
;             for (int ai = 0; ai < 2; ++ai) {
;                 EPI_SCHED();
;                 f32x4 cs[4], sn[4];
;                 if (do_rope) {
; #pragma unroll
;                     for (int m = 0; m < 4; ++m) { const int s = (int)((row0 + ai * 128 + m * 16) & 2047); cs[m] = *(const f32x4*)(rope + s * 16 + i0); sn[m] = *(const f32x4*)(rope + 32768 + s * 16 + i0); }
;                 }
; #pragma unroll
;                 for (int m = 0; m < 4; ++m) {
;                     const size_t row = row0 + ai * 128 + m * 16;
;                     f32x4 a = acc[ai][bj][m][0] * rs[ai][m], b = acc[ai][bj][m][1] * rs[ai][m];
;                     if (do_rope) rope4(a, b, cs[m], sn[m]);
;                     *(u32x4*)(q + row * 1536 + col) = pk8(a, b);
.LBB0_2686:
	s_or_b64 exec, exec, s[4:5]
	v_mul_f32_e32 v0, 0x4b800000, v94
	v_cndmask_b32_e64 v0, v94, v0, s[2:3]
	v_rsq_f32_e32 v0, v0
	v_cvt_pk_bf16_f32 v78, v78, v79
	v_cvt_pk_bf16_f32 v79, v80, v81
	v_cvt_pk_bf16_f32 v80, v74, v75
	v_mul_f32_e32 v74, 0x45800000, v0
	v_cndmask_b32_e64 v74, v0, v74, s[2:3]
	s_mov_b64 s[2:3], 0x78000
	v_cvt_pk_bf16_f32 v81, v76, v77
	v_lshl_add_u64 v[76:77], v[158:159], 0, s[2:3]
	v_lshl_add_u64 v[94:95], v[164:165], 1, v[76:77]
	v_pk_mul_f32 v[72:73], v[72:73], v[74:75] op_sel_hi:[1,0]
	v_pk_mul_f32 v[70:71], v[70:71], v[74:75] op_sel_hi:[1,0]
	v_pk_mul_f32 v[68:69], v[68:69], v[74:75] op_sel_hi:[1,0]
	v_pk_mul_f32 v[66:67], v[66:67], v[74:75] op_sel_hi:[1,0]
	flat_store_dwordx4 v[94:95], v[78:81]
	s_and_saveexec_b64 s[2:3], vcc
	s_cbranch_execz .LBB0_2688
	s_waitcnt vmcnt(3) lgkmcnt(0)
	v_mov_b32_e32 v94, v83
	v_mov_b32_e32 v95, v87
	v_mul_f32_e32 v0, v73, v87
	v_pk_fma_f32 v[94:95], v[72:73], v[94:95], v[0:1] op_sel_hi:[1,1,0] neg_lo:[0,0,1] neg_hi:[0,0,1]
	v_mov_b32_e32 v96, v87
	v_mov_b32_e32 v97, v83
	v_mul_f32_e32 v0, v73, v83
	v_pk_fma_f32 v[96:97], v[72:73], v[96:97], v[0:1] op_sel_hi:[1,1,0]
	v_mov_b32_e32 v120, v85
	v_mov_b32_e32 v121, v89
	v_mul_f32_e32 v0, v69, v89
	v_pk_mul_f32 v[78:79], v[70:71], v[86:87] op_sel:[1,0] op_sel_hi:[0,0]
	v_pk_mul_f32 v[72:73], v[66:67], v[88:89] op_sel:[1,0] op_sel_hi:[0,0]
	v_pk_fma_f32 v[120:121], v[68:69], v[120:121], v[0:1] op_sel_hi:[1,1,0] neg_lo:[0,0,1] neg_hi:[0,0,1]
	v_mov_b32_e32 v134, v89
	v_mov_b32_e32 v135, v85
	v_mul_f32_e32 v0, v69, v85
	v_pk_mul_f32 v[80:81], v[70:71], v[82:83]
	v_pk_fma_f32 v[70:71], v[70:71], v[82:83], v[78:79] op_sel_hi:[1,0,1]
	v_pk_mul_f32 v[118:119], v[66:67], v[84:85]
	v_pk_fma_f32 v[66:67], v[66:67], v[84:85], v[72:73] op_sel_hi:[1,0,1]
	v_pk_fma_f32 v[134:135], v[68:69], v[134:135], v[0:1] op_sel_hi:[1,1,0]
	v_sub_f32_e32 v66, v118, v72
	v_sub_f32_e32 v70, v80, v78
	v_mov_b32_e32 v68, v120
	v_mov_b32_e32 v69, v134
	v_mov_b32_e32 v72, v94
	v_mov_b32_e32 v73, v96
.LBB0_2688:
	s_or_b64 exec, exec, s[2:3]
	s_mov_b64 s[2:3], 0x84000
	v_cvt_pk_bf16_f32 v70, v70, v71
	v_cvt_pk_bf16_f32 v71, v72, v73
	v_cvt_pk_bf16_f32 v72, v66, v67
	v_lshl_add_u64 v[66:67], v[158:159], 0, s[2:3]
	v_cvt_pk_bf16_f32 v73, v68, v69
	v_lshl_add_u64 v[68:69], v[164:165], 1, v[66:67]
	flat_store_dwordx4 v[68:69], v[70:73]
	v_add_u32_e32 v68, 0x80, v164
	s_mov_b32 s2, 0x2aaaaaab
	v_mul_hi_i32 v0, v68, s2
	v_lshrrev_b32_e32 v69, 31, v0
	v_lshrrev_b32_e32 v0, 4, v0
	v_add_u32_e32 v0, v0, v69
	s_movk_i32 s2, 0x60
	v_mul_lo_u32 v0, v0, s2
	v_sub_u32_e32 v0, v68, v0
	v_subrev_u32_e32 v69, 64, v0
	v_lshrrev_b32_e32 v69, 1, v69
	v_cmp_lt_i32_e32 vcc, 63, v0
	s_nop 1
	v_cndmask_b32_e32 v0, 0, v69, vcc
	v_lshlrev_b64 v[70:71], 2, v[0:1]
	v_lshl_add_u64 v[72:73], s[6:7], 0, v[70:71]
	v_lshl_add_u64 v[70:71], s[18:19], 0, v[70:71]
	s_and_saveexec_b64 s[2:3], vcc
	s_cbranch_execz .LBB0_2690
	v_mov_b32_e32 v163, v1
	v_lshl_add_u64 v[78:79], v[72:73], 0, v[162:163]
	v_lshl_add_u64 v[80:81], v[70:71], 0, v[162:163]
	s_waitcnt vmcnt(0) lgkmcnt(0)
	global_load_dwordx4 v[122:125], v[78:79], off
	global_load_dwordx4 v[106:109], v[78:79], off offset:1024
	global_load_dwordx4 v[126:129], v[80:81], off
	global_load_dwordx4 v[110:113], v[80:81], off offset:1024
	global_load_dwordx4 v[98:101], v[78:79], off offset:2048
	global_load_dwordx4 v[82:85], v[78:79], off offset:3072
	global_load_dwordx4 v[102:105], v[80:81], off offset:2048
	global_load_dwordx4 v[86:89], v[80:81], off offset:3072

; DI u32x4 pk8(f32x4 a, f32x4 b) { u32x4 o; o.x = pk2(a.x, a.y); o.y = pk2(a.z, a.w); o.z = pk2(b.x, b.y); o.w = pk2(b.z, b.w); return o; }
; #define EPI_SCHED() __builtin_amdgcn_sched_barrier(0)
;     DI void operator()(const AccT& acc, const Unit& u, int wr, int wc, int fr, int fq) const {
;     ...
;             for (int ai = 0; ai < 2; ++ai) {
;                 EPI_SCHED();
;                 f32x4 cs[4], sn[4];
;                 if (do_rope) {
; #pragma unroll
;                     for (int m = 0; m < 4; ++m) { const int s = (int)((row0 + ai * 128 + m * 16) & 2047); cs[m] = *(const f32x4*)(rope + s * 16 + i0); sn[m] = *(const f32x4*)(rope + 32768 + s * 16 + i0); }
;                 }
; #pragma unroll
;                 for (int m = 0; m < 4; ++m) {
;                     const size_t row = row0 + ai * 128 + m * 16;
;                     f32x4 a = acc[ai][bj][m][0] * rs[ai][m], b = acc[ai][bj][m][1] * rs[ai][m];
;                     if (do_rope) rope4(a, b, cs[m], sn[m]);
;                     *(u32x4*)(q + row * 1536 + col) = pk8(a, b);
;                 }
.LBB0_2692:
	s_or_b64 exec, exec, s[2:3]
	v_mov_b32_e32 v155, v154
	v_cvt_pk_bf16_f32 v62, v62, v63
	v_cvt_pk_bf16_f32 v63, v64, v65
	v_cvt_pk_bf16_f32 v64, v58, v59
	v_mov_b32_e32 v58, v154
	v_mov_b32_e32 v59, v154
	v_cvt_pk_bf16_f32 v65, v60, v61
	v_pk_mul_f32 v[56:57], v[56:57], v[58:59]
	v_pk_mul_f32 v[54:55], v[54:55], v[154:155]
	v_pk_mul_f32 v[52:53], v[52:53], v[58:59]
	v_pk_mul_f32 v[50:51], v[50:51], v[154:155]
	flat_store_dwordx4 v[156:157], v[62:65] offset:256
	s_and_saveexec_b64 s[2:3], vcc
	s_cbranch_execz .LBB0_2694
	s_waitcnt vmcnt(3) lgkmcnt(0)
	v_mov_b32_e32 v62, v107
	v_mov_b32_e32 v63, v111
	v_mul_f32_e32 v0, v57, v111
	v_pk_fma_f32 v[62:63], v[56:57], v[62:63], v[0:1] op_sel_hi:[1,1,0] neg_lo:[0,0,1] neg_hi:[0,0,1]
	v_mov_b32_e32 v64, v111
	v_mov_b32_e32 v65, v107
	v_mul_f32_e32 v0, v57, v107
	v_pk_fma_f32 v[64:65], v[56:57], v[64:65], v[0:1] op_sel_hi:[1,1,0]
	v_mov_b32_e32 v80, v109
	v_mov_b32_e32 v81, v113
	v_mul_f32_e32 v0, v53, v113
	v_pk_mul_f32 v[58:59], v[54:55], v[110:111] op_sel:[1,0] op_sel_hi:[0,0]
	v_pk_mul_f32 v[56:57], v[50:51], v[112:113] op_sel:[1,0] op_sel_hi:[0,0]
	v_pk_fma_f32 v[80:81], v[52:53], v[80:81], v[0:1] op_sel_hi:[1,1,0] neg_lo:[0,0,1] neg_hi:[0,0,1]
	v_mov_b32_e32 v94, v113
	v_mov_b32_e32 v95, v109
	v_mul_f32_e32 v0, v53, v109
	v_pk_mul_f32 v[60:61], v[54:55], v[106:107]
	v_pk_fma_f32 v[54:55], v[54:55], v[106:107], v[58:59] op_sel_hi:[1,0,1]
	v_pk_mul_f32 v[78:79], v[50:51], v[108:109]
	v_pk_fma_f32 v[50:51], v[50:51], v[108:109], v[56:57] op_sel_hi:[1,0,1]
	v_pk_fma_f32 v[94:95], v[52:53], v[94:95], v[0:1] op_sel_hi:[1,1,0]
	v_sub_f32_e32 v50, v78, v56
	v_sub_f32_e32 v54, v60, v58
	v_mov_b32_e32 v52, v80
	v_mov_b32_e32 v53, v94
	v_mov_b32_e32 v56, v62
	v_mov_b32_e32 v57, v64
.LBB0_2694:
	s_or_b64 exec, exec, s[2:3]
	v_ashrrev_i32_e32 v69, 31, v68
	v_cvt_pk_bf16_f32 v54, v54, v55
	v_cvt_pk_bf16_f32 v55, v56, v57
	v_cvt_pk_bf16_f32 v56, v50, v51
	v_cvt_pk_bf16_f32 v57, v52, v53
	v_lshl_add_u64 v[50:51], v[68:69], 1, v[148:149]
	v_mov_b32_e32 v147, v146
	flat_store_dwordx4 v[50:51], v[54:57]
	v_mov_b32_e32 v50, v146
	v_mov_b32_e32 v51, v146
	v_pk_mul_f32 v[48:49], v[48:49], v[50:51]
	v_pk_mul_f32 v[46:47], v[46:47], v[146:147]
	v_pk_mul_f32 v[44:45], v[44:45], v[50:51]
	v_pk_mul_f32 v[42:43], v[42:43], v[146:147]
	s_and_saveexec_b64 s[2:3], vcc
	s_cbranch_execz .LBB0_2696
	s_waitcnt vmcnt(3) lgkmcnt(0)
	v_mov_b32_e32 v54, v99
	v_mov_b32_e32 v55, v103
	v_mul_f32_e32 v0, v49, v103
	v_pk_fma_f32 v[54:55], v[48:49], v[54:55], v[0:1] op_sel_hi:[1,1,0] neg_lo:[0,0,1] neg_hi:[0,0,1]
	v_mov_b32_e32 v56, v103
	v_mov_b32_e32 v57, v99
	v_mul_f32_e32 v0, v49, v99
	v_pk_fma_f32 v[56:57], v[48:49], v[56:57], v[0:1] op_sel_hi:[1,1,0]
	v_mov_b32_e32 v60, v101
	v_mov_b32_e32 v61, v105
	v_mul_f32_e32 v0, v45, v105
	v_pk_mul_f32 v[50:51], v[46:47], v[102:103] op_sel:[1,0] op_sel_hi:[0,0]
	v_pk_mul_f32 v[48:49], v[42:43], v[104:105] op_sel:[1,0] op_sel_hi:[0,0]
	v_pk_fma_f32 v[60:61], v[44:45], v[60:61], v[0:1] op_sel_hi:[1,1,0] neg_lo:[0,0,1] neg_hi:[0,0,1]
	v_mov_b32_e32 v62, v105
	v_mov_b32_e32 v63, v101
	v_mul_f32_e32 v0, v45, v101
	v_pk_mul_f32 v[52:53], v[46:47], v[98:99]
	v_pk_fma_f32 v[46:47], v[46:47], v[98:99], v[50:51] op_sel_hi:[1,0,1]
	v_pk_mul_f32 v[58:59], v[42:43], v[100:101]
	v_pk_fma_f32 v[42:43], v[42:43], v[100:101], v[48:49] op_sel_hi:[1,0,1]
	v_pk_fma_f32 v[62:63], v[44:45], v[62:63], v[0:1] op_sel_hi:[1,1,0]
	v_sub_f32_e32 v42, v58, v48
	v_sub_f32_e32 v46, v52, v50
	v_mov_b32_e32 v44, v60
	v_mov_b32_e32 v45, v62
	v_mov_b32_e32 v48, v54
	v_mov_b32_e32 v49, v56
.LBB0_2696:
	s_or_b64 exec, exec, s[2:3]
	v_cvt_pk_bf16_f32 v46, v46, v47
	v_cvt_pk_bf16_f32 v47, v48, v49
	v_cvt_pk_bf16_f32 v48, v42, v43
	v_cvt_pk_bf16_f32 v49, v44, v45
	v_lshl_add_u64 v[42:43], v[68:69], 1, v[140:141]
	v_mov_b32_e32 v139, v138
	flat_store_dwordx4 v[42:43], v[46:49]
	v_mov_b32_e32 v42, v138
	v_mov_b32_e32 v43, v138
	v_pk_mul_f32 v[40:41], v[40:41], v[42:43]
	v_pk_mul_f32 v[38:39], v[38:39], v[138:139]
	v_pk_mul_f32 v[36:37], v[36:37], v[42:43]
	v_pk_mul_f32 v[34:35], v[34:35], v[138:139]
	s_and_saveexec_b64 s[2:3], vcc
	s_cbranch_execz .LBB0_2698
	s_waitcnt vmcnt(3) lgkmcnt(0)
	v_mov_b32_e32 v46, v83
	v_mov_b32_e32 v47, v87
	v_mul_f32_e32 v0, v41, v87
	v_pk_fma_f32 v[46:47], v[40:41], v[46:47], v[0:1] op_sel_hi:[1,1,0] neg_lo:[0,0,1] neg_hi:[0,0,1]
	v_mov_b32_e32 v48, v87
	v_mov_b32_e32 v49, v83
	v_mul_f32_e32 v0, v41, v83
	v_pk_fma_f32 v[48:49], v[40:41], v[48:49], v[0:1] op_sel_hi:[1,1,0]
	v_mov_b32_e32 v52, v85
	v_mov_b32_e32 v53, v89
	v_mul_f32_e32 v0, v37, v89
	v_pk_mul_f32 v[42:43], v[38:39], v[86:87] op_sel:[1,0] op_sel_hi:[0,0]
	v_pk_mul_f32 v[40:41], v[34:35], v[88:89] op_sel:[1,0] op_sel_hi:[0,0]
	v_pk_fma_f32 v[52:53], v[36:37], v[52:53], v[0:1] op_sel_hi:[1,1,0] neg_lo:[0,0,1] neg_hi:[0,0,1]
	v_mov_b32_e32 v54, v89
	v_mov_b32_e32 v55, v85
	v_mul_f32_e32 v0, v37, v85
	v_pk_mul_f32 v[44:45], v[38:39], v[82:83]
	v_pk_fma_f32 v[38:39], v[38:39], v[82:83], v[42:43] op_sel_hi:[1,0,1]
	v_pk_mul_f32 v[50:51], v[34:35], v[84:85]
	v_pk_fma_f32 v[34:35], v[34:35], v[84:85], v[40:41] op_sel_hi:[1,0,1]
	v_pk_fma_f32 v[54:55], v[36:37], v[54:55], v[0:1] op_sel_hi:[1,1,0]
	v_sub_f32_e32 v34, v50, v40
	v_sub_f32_e32 v38, v44, v42
	v_mov_b32_e32 v36, v52
	v_mov_b32_e32 v37, v54
	v_mov_b32_e32 v40, v46
	v_mov_b32_e32 v41, v48
.LBB0_2698:
	s_or_b64 exec, exec, s[2:3]
	v_cvt_pk_bf16_f32 v38, v38, v39
	v_cvt_pk_bf16_f32 v39, v40, v41
	v_cvt_pk_bf16_f32 v40, v34, v35
	v_cvt_pk_bf16_f32 v41, v36, v37
	v_lshl_add_u64 v[34:35], v[68:69], 1, v[130:131]
	flat_store_dwordx4 v[34:35], v[38:41]
	s_and_saveexec_b64 s[2:3], vcc
	s_cbranch_execz .LBB0_2700
	v_lshlrev_b32_e32 v0, 2, v133
	v_lshl_add_u64 v[34:35], v[72:73], 0, v[0:1]
	v_lshl_add_u64 v[36:37], v[70:71], 0, v[0:1]
	s_waitcnt vmcnt(0) lgkmcnt(0)
	global_load_dwordx4 v[122:125], v[34:35], off
	global_load_dwordx4 v[106:109], v[34:35], off offset:1024
	global_load_dwordx4 v[126:129], v[36:37], off
	global_load_dwordx4 v[110:113], v[36:37], off offset:1024
	global_load_dwordx4 v[98:101], v[34:35], off offset:2048
	global_load_dwordx4 v[82:85], v[34:35], off offset:3072
	global_load_dwordx4 v[102:105], v[36:37], off offset:2048
	global_load_dwordx4 v[86:89], v[36:37], off offset:3072

; DI u32x4 pk8(f32x4 a, f32x4 b) { u32x4 o; o.x = pk2(a.x, a.y); o.y = pk2(a.z, a.w); o.z = pk2(b.x, b.y); o.w = pk2(b.z, b.w); return o; }
;     DI void operator()(const AccT& acc, const Unit& u, int wr, int wc, int fr, int fq) const {
;     ...
;                 for (int m = 0; m < 4; ++m) {
;                     const size_t row = row0 + ai * 128 + m * 16;
;                     f32x4 a = acc[ai][bj][m][0] * rs[ai][m], b = acc[ai][bj][m][1] * rs[ai][m];
;                     if (do_rope) rope4(a, b, cs[m], sn[m]);
;                     *(u32x4*)(q + row * 1536 + col) = pk8(a, b);
;                 }
.LBB0_2702:
	s_or_b64 exec, exec, s[2:3]
	v_cvt_pk_bf16_f32 v30, v30, v31
	v_cvt_pk_bf16_f32 v31, v32, v33
	v_cvt_pk_bf16_f32 v32, v26, v27
	v_cvt_pk_bf16_f32 v33, v28, v29
	v_lshl_add_u64 v[26:27], v[68:69], 1, v[116:117]
	v_mov_b32_e32 v115, v114
	flat_store_dwordx4 v[26:27], v[30:33]
	v_mov_b32_e32 v26, v114
	v_mov_b32_e32 v27, v114
	v_pk_mul_f32 v[24:25], v[24:25], v[26:27]
	v_pk_mul_f32 v[22:23], v[22:23], v[114:115]
	v_pk_mul_f32 v[20:21], v[20:21], v[26:27]
	v_pk_mul_f32 v[18:19], v[18:19], v[114:115]
	s_and_saveexec_b64 s[2:3], vcc
	s_cbranch_execz .LBB0_2704
	s_waitcnt vmcnt(3) lgkmcnt(0)
	v_pk_mul_f32 v[26:27], v[22:23], v[110:111] op_sel:[1,0] op_sel_hi:[0,0]
	v_mov_b32_e32 v110, v107
	v_mul_f32_e32 v0, v25, v111
	v_pk_mul_f32 v[28:29], v[22:23], v[106:107]
	v_pk_fma_f32 v[22:23], v[22:23], v[106:107], v[26:27] op_sel_hi:[1,0,1]
	v_pk_fma_f32 v[30:31], v[24:25], v[110:111], v[0:1] op_sel_hi:[1,1,0] neg_lo:[0,0,1] neg_hi:[0,0,1]
	v_mov_b32_e32 v106, v111
	v_mul_f32_e32 v0, v25, v107
	v_pk_fma_f32 v[32:33], v[24:25], v[106:107], v[0:1] op_sel_hi:[1,1,0]
	v_pk_mul_f32 v[24:25], v[18:19], v[112:113] op_sel:[1,0] op_sel_hi:[0,0]
	v_mov_b32_e32 v112, v109
	v_mul_f32_e32 v0, v21, v113
	v_pk_mul_f32 v[34:35], v[18:19], v[108:109]
	v_pk_fma_f32 v[18:19], v[18:19], v[108:109], v[24:25] op_sel_hi:[1,0,1]
	v_pk_fma_f32 v[36:37], v[20:21], v[112:113], v[0:1] op_sel_hi:[1,1,0] neg_lo:[0,0,1] neg_hi:[0,0,1]
	v_mov_b32_e32 v108, v113
	v_mul_f32_e32 v0, v21, v109
	v_pk_fma_f32 v[38:39], v[20:21], v[108:109], v[0:1] op_sel_hi:[1,1,0]
	v_sub_f32_e32 v18, v34, v24
	v_sub_f32_e32 v22, v28, v26
	v_mov_b32_e32 v20, v36
	v_mov_b32_e32 v21, v38
	v_mov_b32_e32 v24, v30
	v_mov_b32_e32 v25, v32
.LBB0_2704:
	s_or_b64 exec, exec, s[2:3]
	v_cvt_pk_bf16_f32 v22, v22, v23
	v_cvt_pk_bf16_f32 v23, v24, v25
	v_cvt_pk_bf16_f32 v24, v18, v19
	v_cvt_pk_bf16_f32 v25, v20, v21
	v_lshl_add_u64 v[18:19], v[68:69], 1, v[92:93]
	v_mov_b32_e32 v91, v90
	flat_store_dwordx4 v[18:19], v[22:25]
	v_mov_b32_e32 v18, v90
	v_mov_b32_e32 v19, v90
	v_pk_mul_f32 v[16:17], v[16:17], v[18:19]
	v_pk_mul_f32 v[14:15], v[14:15], v[90:91]
	v_pk_mul_f32 v[12:13], v[12:13], v[18:19]
	v_pk_mul_f32 v[10:11], v[10:11], v[90:91]
	s_and_saveexec_b64 s[2:3], vcc
	s_cbranch_execz .LBB0_2706
	s_waitcnt vmcnt(3) lgkmcnt(0)
	v_pk_mul_f32 v[18:19], v[14:15], v[102:103] op_sel:[1,0] op_sel_hi:[0,0]
	v_mov_b32_e32 v102, v99
	v_mul_f32_e32 v0, v17, v103
	v_pk_mul_f32 v[20:21], v[14:15], v[98:99]
	v_pk_fma_f32 v[14:15], v[14:15], v[98:99], v[18:19] op_sel_hi:[1,0,1]
	v_pk_fma_f32 v[22:23], v[16:17], v[102:103], v[0:1] op_sel_hi:[1,1,0] neg_lo:[0,0,1] neg_hi:[0,0,1]
	v_mov_b32_e32 v98, v103
	v_mul_f32_e32 v0, v17, v99
	v_pk_fma_f32 v[24:25], v[16:17], v[98:99], v[0:1] op_sel_hi:[1,1,0]
	v_pk_mul_f32 v[16:17], v[10:11], v[104:105] op_sel:[1,0] op_sel_hi:[0,0]
	v_mov_b32_e32 v104, v101
	v_mul_f32_e32 v0, v13, v105
	v_pk_mul_f32 v[26:27], v[10:11], v[100:101]
	v_pk_fma_f32 v[10:11], v[10:11], v[100:101], v[16:17] op_sel_hi:[1,0,1]
	v_pk_fma_f32 v[28:29], v[12:13], v[104:105], v[0:1] op_sel_hi:[1,1,0] neg_lo:[0,0,1] neg_hi:[0,0,1]
	v_mov_b32_e32 v100, v105
	v_mul_f32_e32 v0, v13, v101
	v_pk_fma_f32 v[30:31], v[12:13], v[100:101], v[0:1] op_sel_hi:[1,1,0]
	v_sub_f32_e32 v10, v26, v16
	v_sub_f32_e32 v14, v20, v18
	v_mov_b32_e32 v12, v28
	v_mov_b32_e32 v13, v30
	v_mov_b32_e32 v16, v22
	v_mov_b32_e32 v17, v24
.LBB0_2706:
	s_or_b64 exec, exec, s[2:3]
	v_cvt_pk_bf16_f32 v14, v14, v15
	v_cvt_pk_bf16_f32 v15, v16, v17
	v_cvt_pk_bf16_f32 v16, v10, v11
	v_cvt_pk_bf16_f32 v17, v12, v13
	v_lshl_add_u64 v[10:11], v[68:69], 1, v[76:77]
	v_mov_b32_e32 v75, v74
	flat_store_dwordx4 v[10:11], v[14:17]
	v_mov_b32_e32 v10, v74
	v_mov_b32_e32 v11, v74
	v_pk_mul_f32 v[8:9], v[8:9], v[10:11]
	v_pk_mul_f32 v[6:7], v[6:7], v[74:75]
	v_pk_mul_f32 v[4:5], v[4:5], v[10:11]
	v_pk_mul_f32 v[2:3], v[2:3], v[74:75]
	s_and_saveexec_b64 s[2:3], vcc
	s_cbranch_execz .LBB0_2708
	s_waitcnt vmcnt(3) lgkmcnt(0)
	v_pk_mul_f32 v[10:11], v[6:7], v[86:87] op_sel:[1,0] op_sel_hi:[0,0]
	v_mov_b32_e32 v86, v83
	v_mul_f32_e32 v0, v9, v87
	v_pk_mul_f32 v[12:13], v[6:7], v[82:83]
	v_pk_fma_f32 v[6:7], v[6:7], v[82:83], v[10:11] op_sel_hi:[1,0,1]
	v_pk_fma_f32 v[14:15], v[8:9], v[86:87], v[0:1] op_sel_hi:[1,1,0] neg_lo:[0,0,1] neg_hi:[0,0,1]
	v_mov_b32_e32 v82, v87
	v_mul_f32_e32 v0, v9, v83
	v_pk_fma_f32 v[16:17], v[8:9], v[82:83], v[0:1] op_sel_hi:[1,1,0]
	v_pk_mul_f32 v[8:9], v[2:3], v[88:89] op_sel:[1,0] op_sel_hi:[0,0]
	v_mov_b32_e32 v88, v85
	v_mul_f32_e32 v0, v5, v89
	v_pk_mul_f32 v[18:19], v[2:3], v[84:85]
	v_pk_fma_f32 v[2:3], v[2:3], v[84:85], v[8:9] op_sel_hi:[1,0,1]
	v_pk_fma_f32 v[20:21], v[4:5], v[88:89], v[0:1] op_sel_hi:[1,1,0] neg_lo:[0,0,1] neg_hi:[0,0,1]
	v_mov_b32_e32 v84, v89
	v_mul_f32_e32 v0, v5, v85
	v_pk_fma_f32 v[22:23], v[4:5], v[84:85], v[0:1] op_sel_hi:[1,1,0]
	v_sub_f32_e32 v2, v18, v8
	v_sub_f32_e32 v6, v12, v10
	v_mov_b32_e32 v4, v20
	v_mov_b32_e32 v5, v22
	v_mov_b32_e32 v8, v14
	v_mov_b32_e32 v9, v16

; #define PG8_STAGE(bufoff, gbase, voff) do { const char* _gb = (const char*)(gbase); asm volatile("" : "+s"(_gb)); _Pragma("unroll") for (int _i = 0; _i < 2; ++_i) { \
;         unsigned _vo = (voff)[_i]; asm volatile("" : "+v"(_vo));     \
;         __builtin_amdgcn_global_load_lds((const unsigned*)(_gb + _vo), (LAS unsigned*)(lds + (bufoff) + ldsw + _i * 8192), 16, 0, 0); } } while (0)
; #define PG8_LDA(dst, b, h) do { _Pragma("unroll") for (int m = 0; m < 4; ++m) _Pragma("unroll") for (int k = 0; k < 2; ++k) dst[m][k] = *(const LAS bf16x8*)(lds + PG8_SA(b, h) + aoff + m * 2048 + k * 1024); } while (0)
; #define PG8_LDB(dst, b, h) do { _Pragma("unroll") for (int n = 0; n < 2; ++n) _Pragma("unroll") for (int k = 0; k < 2; ++k) dst[n][k] = *(const LAS bf16x8*)(lds + PG8_SB(b, h) + boff + n * 2048 + k * 1024); } while (0)
; #define PG8_WAIT_V(n) asm volatile("s_waitcnt vmcnt(" #n ")" ::: "memory")
; #define PG8_WAIT_L(n) asm volatile("s_waitcnt lgkmcnt(" #n ")" ::: "memory")
; #define PG8_BAR __builtin_amdgcn_s_barrier()
; #define PG8_SCHED __builtin_amdgcn_sched_barrier(0)
; template <class Epi, class Sched>
; DI void gemm_phase(int wv, LAS unsigned char* lds, const Gemm g, const Sched& S, const Epi& E) {
;     ...
;             const bool last = (t == nt - 2);
;             const char* a1 = cA + (size_t)(t + 1) * kstep;
;             const char* a2 = last ? nA : cA + (size_t)(t + 2) * kstep; const char* b2 = last ? nB : cB + (size_t)(t + 2) * kstep;
;             const char* a3 = a2 + kstep; const char* b3 = b2 + kstep;
;             PG8_LDB(B0, 0, 0); PG8_LDB(B1, 0, 1); PG8_SCHED; PG8_LDA(At, 0, 0); PG8_STAGE(PG8_SA(1, 1), a1 + hstepA, voffA);
;             PG8_WAIT_V(8); PG8_WAIT_L(0); PG8_BAR; PG8_MMA(0, 0, At, B0); PG8_MMA(0, 1, At, B1); PG8_BAR; PG8_SCHED;
;             PG8_LDA(At, 0, 1); PG8_STAGE(PG8_SB(0, 0), b2, voffB); PG8_STAGE(PG8_SB(0, 1), b2 + hstepB, voffB); PG8_STAGE(PG8_SA(0, 0), a2, voffA);
;             PG8_WAIT_V(8); PG8_WAIT_L(0); PG8_BAR; PG8_MMA(1, 0, At, B0); PG8_MMA(1, 1, At, B1); PG8_BAR; PG8_SCHED;
;     ...
; #pragma unroll
;         for (int a = 0; a < 2; ++a)
; #pragma unroll
;             for (int b = 0; b < 2; ++b)
; #pragma unroll
;                 for (int m = 0; m < 4; ++m)
; #pragma unroll
;                     for (int n = 0; n < 2; ++n) acc[a][b][m][n] = (f32x4){0.f, 0.f, 0.f, 0.f};
.LBB0_2949:
	s_add_u32 s23, s24, 0x100
	s_addc_u32 s65, s25, 0
	s_add_u32 s66, s26, 0x100
	s_addc_u32 s67, s27, 0
	s_mov_b32 s24, 0
	s_waitcnt lgkmcnt(0)
	s_waitcnt vmcnt(0)
	s_add_i32 s84, s24, 2
	s_cmp_eq_u32 s55, s24
	s_cselect_b32 s28, s18, s66
	s_cselect_b32 s29, s19, s67
	s_cselect_b32 s26, s20, s23
	s_cselect_b32 s27, s21, s65
	s_add_u32 s24, s28, 0x80
	s_addc_u32 s25, s29, 0
	s_add_i32 s70, 0, 0x10000
	s_add_i32 s78, 0, 0x14000
	v_add_u32_e32 v142, s70, v175
	v_add_u32_e32 v158, s78, v175
	ds_read_b128 v[130:133], v142
	ds_read_b128 v[134:137], v142 offset:1024
	ds_read_b128 v[138:141], v142 offset:2048
	ds_read_b128 v[142:145], v142 offset:3072
	ds_read_b128 v[146:149], v158
	ds_read_b128 v[150:153], v158 offset:1024
	ds_read_b128 v[154:157], v158 offset:2048
	ds_read_b128 v[158:161], v158 offset:3072
	s_add_u32 s30, s66, s36
	s_addc_u32 s31, s67, 0
	s_add_u32 s30, s30, 0xffffff80
	s_addc_u32 s31, s31, -1
	v_mov_b32_e32 v170, v0
	ds_read_b128 v[162:165], v176
	ds_read_b128 v[166:169], v176 offset:1024
	ds_read_b128 v[178:181], v176 offset:2048
	ds_read_b128 v[182:185], v176 offset:3072
	ds_read_b128 v[186:189], v176 offset:4096
	ds_read_b128 v[190:193], v176 offset:5120
	ds_read_b128 v[194:197], v176 offset:6144
	ds_read_b128 v[198:201], v176 offset:7168
	s_add_i32 m0, s39, 0xc000
	s_nop 0
	global_load_lds_dwordx4 v170, s[30:31]
	v_mov_b32_e32 v170, v173
	s_add_i32 m0, s39, 0xe000
	s_nop 0
	global_load_lds_dwordx4 v170, s[30:31]
	s_waitcnt vmcnt(8)
	s_waitcnt lgkmcnt(0)
	s_barrier
	s_setprio 1
	s_waitcnt lgkmcnt(0)
	v_mfma_f32_16x16x32_bf16 v[126:129], v[130:133], v[162:165], 0
	v_mfma_f32_16x16x32_bf16 v[122:125], v[138:141], v[162:165], 0
	v_mfma_f32_16x16x32_bf16 v[110:113], v[130:133], v[178:181], 0
	v_mfma_f32_16x16x32_bf16 v[106:109], v[138:141], v[178:181], 0
	v_mfma_f32_16x16x32_bf16 v[94:97], v[130:133], v[186:189], 0
	v_mfma_f32_16x16x32_bf16 v[90:93], v[138:141], v[186:189], 0
	v_mfma_f32_16x16x32_bf16 v[78:81], v[130:133], v[194:197], 0
	v_mfma_f32_16x16x32_bf16 v[74:77], v[138:141], v[194:197], 0
	v_mfma_f32_16x16x32_bf16 v[126:129], v[134:137], v[166:169], v[126:129]
	v_mfma_f32_16x16x32_bf16 v[122:125], v[142:145], v[166:169], v[122:125]
	v_mfma_f32_16x16x32_bf16 v[110:113], v[134:137], v[182:185], v[110:113]
	v_mfma_f32_16x16x32_bf16 v[106:109], v[142:145], v[182:185], v[106:109]
	v_mfma_f32_16x16x32_bf16 v[94:97], v[134:137], v[190:193], v[94:97]
	v_mfma_f32_16x16x32_bf16 v[90:93], v[142:145], v[190:193], v[90:93]
	v_mfma_f32_16x16x32_bf16 v[78:81], v[134:137], v[198:201], v[78:81]
	v_mfma_f32_16x16x32_bf16 v[74:77], v[142:145], v[198:201], v[74:77]
	s_setprio 0
	s_setprio 1
	v_mfma_f32_16x16x32_bf16 v[118:121], v[146:149], v[162:165], 0
	v_mfma_f32_16x16x32_bf16 v[114:117], v[154:157], v[162:165], 0
	v_mfma_f32_16x16x32_bf16 v[102:105], v[146:149], v[178:181], 0
	v_mfma_f32_16x16x32_bf16 v[98:101], v[154:157], v[178:181], 0
	v_mfma_f32_16x16x32_bf16 v[86:89], v[146:149], v[186:189], 0
	v_mfma_f32_16x16x32_bf16 v[82:85], v[154:157], v[186:189], 0
	v_mfma_f32_16x16x32_bf16 v[70:73], v[146:149], v[194:197], 0
	v_mfma_f32_16x16x32_bf16 v[66:69], v[154:157], v[194:197], 0
	v_mfma_f32_16x16x32_bf16 v[118:121], v[150:153], v[166:169], v[118:121]
	v_mfma_f32_16x16x32_bf16 v[114:117], v[158:161], v[166:169], v[114:117]
	v_mfma_f32_16x16x32_bf16 v[102:105], v[150:153], v[182:185], v[102:105]
	v_mfma_f32_16x16x32_bf16 v[98:101], v[158:161], v[182:185], v[98:101]
	v_mfma_f32_16x16x32_bf16 v[86:89], v[150:153], v[190:193], v[86:89]
	v_mfma_f32_16x16x32_bf16 v[82:85], v[158:161], v[190:193], v[82:85]
	v_mfma_f32_16x16x32_bf16 v[70:73], v[150:153], v[198:201], v[70:73]
	v_mfma_f32_16x16x32_bf16 v[66:69], v[158:161], v[198:201], v[66:69]
	s_setprio 0
	s_barrier
	s_mov_b64 s[30:31], s[26:27]
	v_mov_b32_e32 v170, v172
	s_add_i32 s70, s70, s38
	ds_read_b128 v[162:165], v176 offset:16384
	ds_read_b128 v[166:169], v176 offset:17408
	ds_read_b128 v[178:181], v176 offset:18432
	ds_read_b128 v[182:185], v176 offset:19456
	ds_read_b128 v[186:189], v176 offset:20480
	ds_read_b128 v[190:193], v176 offset:21504
	ds_read_b128 v[194:197], v176 offset:22528
	ds_read_b128 v[198:201], v176 offset:23552
	s_mov_b32 m0, s70
	s_nop 0
	global_load_lds_dwordx4 v170, s[30:31]
	v_mov_b32_e32 v170, v174
	s_add_i32 m0, s70, 0x2000
	s_nop 0
	global_load_lds_dwordx4 v170, s[30:31]
	s_add_u32 s30, s26, s36
	s_addc_u32 s31, s27, 0
	s_mov_b64 s[70:71], s[30:31]
	v_mov_b32_e32 v170, v172
	s_add_i32 s78, s78, s38
	s_mov_b32 m0, s78
	s_nop 0
	global_load_lds_dwordx4 v170, s[70:71]
	v_mov_b32_e32 v170, v174
	s_add_i32 m0, s78, 0x2000
	s_nop 0
	global_load_lds_dwordx4 v170, s[70:71]
	s_mov_b64 s[70:71], s[28:29]
	v_mov_b32_e32 v170, v0
	s_mov_b32 m0, s39
	s_nop 0
	global_load_lds_dwordx4 v170, s[70:71]
	v_mov_b32_e32 v170, v173
	s_mov_b32 m0, s44
	s_nop 0
	global_load_lds_dwordx4 v170, s[70:71]
	s_waitcnt vmcnt(8)
	s_waitcnt lgkmcnt(0)
	s_barrier
; #define PG8_STAGE(bufoff, gbase, voff) do { const char* _gb = (const char*)(gbase); asm volatile("" : "+s"(_gb)); _Pragma("unroll") for (int _i = 0; _i < 2; ++_i) { \
;         unsigned _vo = (voff)[_i]; asm volatile("" : "+v"(_vo));     \
;         __builtin_amdgcn_global_load_lds((const unsigned*)(_gb + _vo), (LAS unsigned*)(lds + (bufoff) + ldsw + _i * 8192), 16, 0, 0); } } while (0)
; #define PG8_LDA(dst, b, h) do { _Pragma("unroll") for (int m = 0; m < 4; ++m) _Pragma("unroll") for (int k = 0; k < 2; ++k) dst[m][k] = *(const LAS bf16x8*)(lds + PG8_SA(b, h) + aoff + m * 2048 + k * 1024); } while (0)
; #define PG8_LDB(dst, b, h) do { _Pragma("unroll") for (int n = 0; n < 2; ++n) _Pragma("unroll") for (int k = 0; k < 2; ++k) dst[n][k] = *(const LAS bf16x8*)(lds + PG8_SB(b, h) + boff + n * 2048 + k * 1024); } while (0)
; #define PG8_MMA(ai, bj, At, Bt) do { __builtin_amdgcn_s_setprio(1); _Pragma("unroll") for (int m = 0; m < 4; ++m) _Pragma("unroll") for (int n = 0; n < 2; ++n) _Pragma("unroll") for (int k = 0; k < 2; ++k) \
;         acc[ai][bj][m][n] = __builtin_amdgcn_mfma_f32_16x16x32_bf16(Bt[n][k], At[m][k], acc[ai][bj][m][n], 0, 0, 0); __builtin_amdgcn_s_setprio(0); } while (0)
; #define PG8_WAIT_V(n) asm volatile("s_waitcnt vmcnt(" #n ")" ::: "memory")
; #define PG8_WAIT_L(n) asm volatile("s_waitcnt lgkmcnt(" #n ")" ::: "memory")
; #define PG8_BAR __builtin_amdgcn_s_barrier()
; #define PG8_SCHED __builtin_amdgcn_sched_barrier(0)
; template <class Epi, class Sched>
; DI void gemm_phase(int wv, LAS unsigned char* lds, const Gemm g, const Sched& S, const Epi& E) {
;     ...
;             PG8_WAIT_V(8); PG8_WAIT_L(0); PG8_BAR; PG8_MMA(1, 0, At, B0); PG8_MMA(1, 1, At, B1); PG8_BAR; PG8_SCHED;
;             PG8_LDB(B0, 1, 0); PG8_LDB(B1, 1, 1); PG8_SCHED; PG8_LDA(At, 1, 0); PG8_STAGE(PG8_SA(0, 1), a2 + hstepA, voffA);
;             PG8_WAIT_V(8); PG8_WAIT_L(0); PG8_BAR; PG8_MMA(0, 0, At, B0); PG8_MMA(0, 1, At, B1); PG8_BAR; PG8_SCHED;
	s_setprio 1
	s_waitcnt lgkmcnt(0)
	v_mfma_f32_16x16x32_bf16 v[62:65], v[130:133], v[162:165], 0
	v_mfma_f32_16x16x32_bf16 v[58:61], v[138:141], v[162:165], 0
	v_mfma_f32_16x16x32_bf16 v[46:49], v[130:133], v[178:181], 0
	v_mfma_f32_16x16x32_bf16 v[42:45], v[138:141], v[178:181], 0
	v_mfma_f32_16x16x32_bf16 v[30:33], v[130:133], v[186:189], 0
	v_mfma_f32_16x16x32_bf16 v[26:29], v[138:141], v[186:189], 0
	v_mfma_f32_16x16x32_bf16 v[14:17], v[130:133], v[194:197], 0
	v_mfma_f32_16x16x32_bf16 v[10:13], v[138:141], v[194:197], 0
	v_mfma_f32_16x16x32_bf16 v[62:65], v[134:137], v[166:169], v[62:65]
	v_mfma_f32_16x16x32_bf16 v[58:61], v[142:145], v[166:169], v[58:61]
	v_mfma_f32_16x16x32_bf16 v[46:49], v[134:137], v[182:185], v[46:49]
	v_mfma_f32_16x16x32_bf16 v[42:45], v[142:145], v[182:185], v[42:45]
	v_mfma_f32_16x16x32_bf16 v[30:33], v[134:137], v[190:193], v[30:33]
	v_mfma_f32_16x16x32_bf16 v[26:29], v[142:145], v[190:193], v[26:29]
	v_mfma_f32_16x16x32_bf16 v[14:17], v[134:137], v[198:201], v[14:17]
	v_mfma_f32_16x16x32_bf16 v[10:13], v[142:145], v[198:201], v[10:13]
	s_setprio 0
	s_setprio 1
	v_mfma_f32_16x16x32_bf16 v[54:57], v[146:149], v[162:165], 0
	v_mfma_f32_16x16x32_bf16 v[50:53], v[154:157], v[162:165], 0
	v_mfma_f32_16x16x32_bf16 v[38:41], v[146:149], v[178:181], 0
	v_mfma_f32_16x16x32_bf16 v[34:37], v[154:157], v[178:181], 0
	v_mfma_f32_16x16x32_bf16 v[22:25], v[146:149], v[186:189], 0
	v_mfma_f32_16x16x32_bf16 v[18:21], v[154:157], v[186:189], 0
	v_mfma_f32_16x16x32_bf16 v[6:9], v[146:149], v[194:197], 0
	v_mfma_f32_16x16x32_bf16 v[2:5], v[154:157], v[194:197], 0
	v_mfma_f32_16x16x32_bf16 v[54:57], v[150:153], v[166:169], v[54:57]
	v_mfma_f32_16x16x32_bf16 v[50:53], v[158:161], v[166:169], v[50:53]
	v_mfma_f32_16x16x32_bf16 v[38:41], v[150:153], v[182:185], v[38:41]
	v_mfma_f32_16x16x32_bf16 v[34:37], v[158:161], v[182:185], v[34:37]
	v_mfma_f32_16x16x32_bf16 v[22:25], v[150:153], v[190:193], v[22:25]
	v_mfma_f32_16x16x32_bf16 v[18:21], v[158:161], v[190:193], v[18:21]
	v_mfma_f32_16x16x32_bf16 v[6:9], v[150:153], v[198:201], v[6:9]
	v_mfma_f32_16x16x32_bf16 v[2:5], v[158:161], v[198:201], v[2:5]
	s_setprio 0
	s_barrier
	s_add_i32 s70, 0, 0x18000
	s_add_i32 s71, 0, 0x1c000
	v_add_u32_e32 v142, s70, v175
	v_add_u32_e32 v158, s71, v175
	ds_read_b128 v[130:133], v142
	ds_read_b128 v[134:137], v142 offset:1024
	ds_read_b128 v[138:141], v142 offset:2048
	ds_read_b128 v[142:145], v142 offset:3072
	ds_read_b128 v[146:149], v158
	ds_read_b128 v[150:153], v158 offset:1024
	ds_read_b128 v[154:157], v158 offset:2048
	ds_read_b128 v[158:161], v158 offset:3072
	s_add_u32 s28, s28, s36
	s_addc_u32 s29, s29, 0
	v_mov_b32_e32 v170, v0
	s_mov_b32 m0, s45
	ds_read_b128 v[162:165], v176 offset:32768
	ds_read_b128 v[166:169], v176 offset:33792
	ds_read_b128 v[178:181], v176 offset:34816
	ds_read_b128 v[182:185], v176 offset:35840
	ds_read_b128 v[186:189], v176 offset:36864
	ds_read_b128 v[190:193], v176 offset:37888
	ds_read_b128 v[194:197], v176 offset:38912
	ds_read_b128 v[198:201], v176 offset:39936
	s_nop 0
	global_load_lds_dwordx4 v170, s[28:29]
	v_mov_b32_e32 v170, v173
	s_mov_b32 m0, s46
	s_nop 0
	global_load_lds_dwordx4 v170, s[28:29]
	s_waitcnt vmcnt(8)
	s_waitcnt lgkmcnt(0)
	s_barrier
	s_setprio 1
	s_waitcnt lgkmcnt(0)
	v_mfma_f32_16x16x32_bf16 v[126:129], v[130:133], v[162:165], v[126:129]
	v_mfma_f32_16x16x32_bf16 v[122:125], v[138:141], v[162:165], v[122:125]
	v_mfma_f32_16x16x32_bf16 v[110:113], v[130:133], v[178:181], v[110:113]
	v_mfma_f32_16x16x32_bf16 v[106:109], v[138:141], v[178:181], v[106:109]
	v_mfma_f32_16x16x32_bf16 v[94:97], v[130:133], v[186:189], v[94:97]
	v_mfma_f32_16x16x32_bf16 v[90:93], v[138:141], v[186:189], v[90:93]
	v_mfma_f32_16x16x32_bf16 v[78:81], v[130:133], v[194:197], v[78:81]
	v_mfma_f32_16x16x32_bf16 v[74:77], v[138:141], v[194:197], v[74:77]
	v_mfma_f32_16x16x32_bf16 v[126:129], v[134:137], v[166:169], v[126:129]
	v_mfma_f32_16x16x32_bf16 v[122:125], v[142:145], v[166:169], v[122:125]
	v_mfma_f32_16x16x32_bf16 v[110:113], v[134:137], v[182:185], v[110:113]
	v_mfma_f32_16x16x32_bf16 v[106:109], v[142:145], v[182:185], v[106:109]
	v_mfma_f32_16x16x32_bf16 v[94:97], v[134:137], v[190:193], v[94:97]
	v_mfma_f32_16x16x32_bf16 v[90:93], v[142:145], v[190:193], v[90:93]
	v_mfma_f32_16x16x32_bf16 v[78:81], v[134:137], v[198:201], v[78:81]
	v_mfma_f32_16x16x32_bf16 v[74:77], v[142:145], v[198:201], v[74:77]
	s_setprio 0
	s_setprio 1
	v_mfma_f32_16x16x32_bf16 v[118:121], v[146:149], v[162:165], v[118:121]
	v_mfma_f32_16x16x32_bf16 v[114:117], v[154:157], v[162:165], v[114:117]
	v_mfma_f32_16x16x32_bf16 v[102:105], v[146:149], v[178:181], v[102:105]
	v_mfma_f32_16x16x32_bf16 v[98:101], v[154:157], v[178:181], v[98:101]
	v_mfma_f32_16x16x32_bf16 v[86:89], v[146:149], v[186:189], v[86:89]
	v_mfma_f32_16x16x32_bf16 v[82:85], v[154:157], v[186:189], v[82:85]
	v_mfma_f32_16x16x32_bf16 v[70:73], v[146:149], v[194:197], v[70:73]
	v_mfma_f32_16x16x32_bf16 v[66:69], v[154:157], v[194:197], v[66:69]
	v_mfma_f32_16x16x32_bf16 v[118:121], v[150:153], v[166:169], v[118:121]
	v_mfma_f32_16x16x32_bf16 v[114:117], v[158:161], v[166:169], v[114:117]
	v_mfma_f32_16x16x32_bf16 v[102:105], v[150:153], v[182:185], v[102:105]
	v_mfma_f32_16x16x32_bf16 v[98:101], v[158:161], v[182:185], v[98:101]
	v_mfma_f32_16x16x32_bf16 v[86:89], v[150:153], v[190:193], v[86:89]
	v_mfma_f32_16x16x32_bf16 v[82:85], v[158:161], v[190:193], v[82:85]
	v_mfma_f32_16x16x32_bf16 v[70:73], v[150:153], v[198:201], v[70:73]
	v_mfma_f32_16x16x32_bf16 v[66:69], v[158:161], v[198:201], v[66:69]
	s_setprio 0
	s_barrier
; #define PG8_STAGE(bufoff, gbase, voff) do { const char* _gb = (const char*)(gbase); asm volatile("" : "+s"(_gb)); _Pragma("unroll") for (int _i = 0; _i < 2; ++_i) { \
;         unsigned _vo = (voff)[_i]; asm volatile("" : "+v"(_vo));     \
;         __builtin_amdgcn_global_load_lds((const unsigned*)(_gb + _vo), (LAS unsigned*)(lds + (bufoff) + ldsw + _i * 8192), 16, 0, 0); } } while (0)
; #define PG8_LDA(dst, b, h) do { _Pragma("unroll") for (int m = 0; m < 4; ++m) _Pragma("unroll") for (int k = 0; k < 2; ++k) dst[m][k] = *(const LAS bf16x8*)(lds + PG8_SA(b, h) + aoff + m * 2048 + k * 1024); } while (0)
; #define PG8_MMA(ai, bj, At, Bt) do { __builtin_amdgcn_s_setprio(1); _Pragma("unroll") for (int m = 0; m < 4; ++m) _Pragma("unroll") for (int n = 0; n < 2; ++n) _Pragma("unroll") for (int k = 0; k < 2; ++k) \
;         acc[ai][bj][m][n] = __builtin_amdgcn_mfma_f32_16x16x32_bf16(Bt[n][k], At[m][k], acc[ai][bj][m][n], 0, 0, 0); __builtin_amdgcn_s_setprio(0); } while (0)
; #define PG8_WAIT_V(n) asm volatile("s_waitcnt vmcnt(" #n ")" ::: "memory")
; #define PG8_WAIT_L(n) asm volatile("s_waitcnt lgkmcnt(" #n ")" ::: "memory")
; #define PG8_BAR __builtin_amdgcn_s_barrier()
; #define PG8_SCHED __builtin_amdgcn_sched_barrier(0)
; template <class Epi, class Sched>
; DI void gemm_phase(int wv, LAS unsigned char* lds, const Gemm g, const Sched& S, const Epi& E) {
;     ...
;             PG8_LDA(At, 1, 1); PG8_STAGE(PG8_SB(1, 0), b3, voffB); PG8_STAGE(PG8_SB(1, 1), b3 + hstepB, voffB); PG8_STAGE(PG8_SA(1, 0), a3, voffA);
;             PG8_WAIT_V(8); PG8_WAIT_L(0); PG8_BAR; PG8_MMA(1, 0, At, B0); PG8_MMA(1, 1, At, B1); PG8_BAR; PG8_SCHED;
;         }
	s_add_u32 s26, s26, 0x80
	s_addc_u32 s27, s27, 0
	v_mov_b32_e32 v170, v172
	s_add_i32 s28, s70, s38
	ds_read_b128 v[162:165], v176 offset:49152
	ds_read_b128 v[166:169], v176 offset:50176
	ds_read_b128 v[178:181], v176 offset:51200
	ds_read_b128 v[182:185], v176 offset:52224
	ds_read_b128 v[186:189], v176 offset:53248
	ds_read_b128 v[190:193], v176 offset:54272
	ds_read_b128 v[194:197], v176 offset:55296
	ds_read_b128 v[198:201], v176 offset:56320
	s_mov_b32 m0, s28
	s_nop 0
	global_load_lds_dwordx4 v170, s[26:27]
	v_mov_b32_e32 v170, v174
	s_add_i32 m0, s28, 0x2000
	s_nop 0
	global_load_lds_dwordx4 v170, s[26:27]
	s_add_u32 s26, s30, 0x80
	s_addc_u32 s27, s31, 0
	v_mov_b32_e32 v170, v172
	s_add_i32 s28, s71, s38
	s_mov_b32 m0, s28
	s_nop 0
	global_load_lds_dwordx4 v170, s[26:27]
	v_mov_b32_e32 v170, v174
	s_add_i32 m0, s28, 0x2000
	s_nop 0
	global_load_lds_dwordx4 v170, s[26:27]
	v_mov_b32_e32 v170, v0
	s_mov_b32 m0, s51
	s_nop 0
	global_load_lds_dwordx4 v170, s[24:25]
	v_mov_b32_e32 v170, v173
	s_mov_b32 m0, s54
	s_nop 0
	global_load_lds_dwordx4 v170, s[24:25]
	s_waitcnt vmcnt(8)
	s_waitcnt lgkmcnt(0)
	s_barrier
	s_setprio 1
	s_waitcnt lgkmcnt(0)
	v_mfma_f32_16x16x32_bf16 v[62:65], v[130:133], v[162:165], v[62:65]
	v_mfma_f32_16x16x32_bf16 v[58:61], v[138:141], v[162:165], v[58:61]
	v_mfma_f32_16x16x32_bf16 v[46:49], v[130:133], v[178:181], v[46:49]
	v_mfma_f32_16x16x32_bf16 v[42:45], v[138:141], v[178:181], v[42:45]
	v_mfma_f32_16x16x32_bf16 v[30:33], v[130:133], v[186:189], v[30:33]
	v_mfma_f32_16x16x32_bf16 v[26:29], v[138:141], v[186:189], v[26:29]
	v_mfma_f32_16x16x32_bf16 v[14:17], v[130:133], v[194:197], v[14:17]
	v_mfma_f32_16x16x32_bf16 v[10:13], v[138:141], v[194:197], v[10:13]
	v_mfma_f32_16x16x32_bf16 v[62:65], v[134:137], v[166:169], v[62:65]
	v_mfma_f32_16x16x32_bf16 v[58:61], v[142:145], v[166:169], v[58:61]
	v_mfma_f32_16x16x32_bf16 v[46:49], v[134:137], v[182:185], v[46:49]
	v_mfma_f32_16x16x32_bf16 v[42:45], v[142:145], v[182:185], v[42:45]
	v_mfma_f32_16x16x32_bf16 v[30:33], v[134:137], v[190:193], v[30:33]
	v_mfma_f32_16x16x32_bf16 v[26:29], v[142:145], v[190:193], v[26:29]
	v_mfma_f32_16x16x32_bf16 v[14:17], v[134:137], v[198:201], v[14:17]
	v_mfma_f32_16x16x32_bf16 v[10:13], v[142:145], v[198:201], v[10:13]
	s_setprio 0
	s_setprio 1
	v_mfma_f32_16x16x32_bf16 v[54:57], v[146:149], v[162:165], v[54:57]
	v_mfma_f32_16x16x32_bf16 v[50:53], v[154:157], v[162:165], v[50:53]
	v_mfma_f32_16x16x32_bf16 v[38:41], v[146:149], v[178:181], v[38:41]
	v_mfma_f32_16x16x32_bf16 v[34:37], v[154:157], v[178:181], v[34:37]
	v_mfma_f32_16x16x32_bf16 v[22:25], v[146:149], v[186:189], v[22:25]
	v_mfma_f32_16x16x32_bf16 v[18:21], v[154:157], v[186:189], v[18:21]
	v_mfma_f32_16x16x32_bf16 v[6:9], v[146:149], v[194:197], v[6:9]
	v_mfma_f32_16x16x32_bf16 v[2:5], v[154:157], v[194:197], v[2:5]
	v_mfma_f32_16x16x32_bf16 v[54:57], v[150:153], v[166:169], v[54:57]
	v_mfma_f32_16x16x32_bf16 v[50:53], v[158:161], v[166:169], v[50:53]
	v_mfma_f32_16x16x32_bf16 v[38:41], v[150:153], v[182:185], v[38:41]
	v_mfma_f32_16x16x32_bf16 v[34:37], v[158:161], v[182:185], v[34:37]
	v_mfma_f32_16x16x32_bf16 v[22:25], v[150:153], v[190:193], v[22:25]
	v_mfma_f32_16x16x32_bf16 v[18:21], v[158:161], v[190:193], v[18:21]
	v_mfma_f32_16x16x32_bf16 v[6:9], v[150:153], v[198:201], v[6:9]
	v_mfma_f32_16x16x32_bf16 v[2:5], v[158:161], v[198:201], v[2:5]
	s_setprio 0
	s_barrier
	s_add_u32 s23, s23, 0x100
	s_addc_u32 s65, s65, 0
	s_add_u32 s66, s66, 0x100
	s_addc_u32 s67, s67, 0
	s_cmp_ge_u32 s84, s48
	s_mov_b32 s24, s84
